# GDN S3 forward substitution hand-written: packed f32 FMAs (same chains, same rounding), L rows prefetched one row ahead in place
# baseline (speedup 1.0000x reference)
; #define LAS __attribute__((address_space(3)))
; DI unsigned pk2(float lo, float hi) { return f2bf(lo) | (f2bf(hi) << 16); }
; DI void gdn_unit(const Params& P, bf16_t* proj, const float* gb, int b, int h, LAS unsigned char* lds) {
;     ...
;             const int blk = lane >> 5, cl = lane & 31;
;             LAS unsigned char* Lbytes = lds + L_OFF;
;             LAS unsigned char* L21b = (LAS unsigned char*)part;
;             {
;                 const int r = lane >> 1, hh = lane & 1;
;                 f32x4 x[4];
; #pragma unroll
;                 for (int q = 0; q < 4; ++q) x[q] = *(const LAS f32x4*)(Lm + (32 + r) * 64 + hh * 16 + q * 4);
;                 u32x4 w0, w1;
;                 w0.x = pk2(x[0][0], x[0][1]); w0.y = pk2(x[0][2], x[0][3]); w0.z = pk2(x[1][0], x[1][1]); w0.w = pk2(x[1][2], x[1][3]);
;                 w1.x = pk2(x[2][0], x[2][1]); w1.y = pk2(x[2][2], x[2][3]); w1.z = pk2(x[3][0], x[3][1]); w1.w = pk2(x[3][2], x[3][3]);
;                 *(LAS u32x4*)(L21b + r * 64 + hh * 32) = w0; *(LAS u32x4*)(L21b + r * 64 + hh * 32 + 16) = w1;
;             }
;             const LAS float* Lblk = Lm + blk * (32 * 64 + 32);
;             float Tc[32];
; #pragma unroll
;             for (int i = 0; i < 32; ++i) {
;                 float s0 = (cl == i) ? 1.0f : 0.0f, s1 = 0.f, s2 = 0.f, s3 = 0.f;
;                 f32x4 lr[8];
; #pragma unroll
;                 for (int j4 = 0; j4 < (i + 3) / 4; ++j4) lr[j4] = *(const LAS f32x4*)(Lblk + i * 64 + j4 * 4);
;                 __builtin_amdgcn_sched_barrier(0);
; #pragma unroll
;                 for (int j4 = 0; j4 < (i + 3) / 4; ++j4) {
;                     const f32x4 l4 = lr[j4];
;                     if (j4 * 4 + 0 < i) s0 -= l4[0] * Tc[j4 * 4 + 0];
;                     if (j4 * 4 + 1 < i) s1 -= l4[1] * Tc[j4 * 4 + 1];
;                     if (j4 * 4 + 2 < i) s2 -= l4[2] * Tc[j4 * 4 + 2];
;                     if (j4 * 4 + 3 < i) s3 -= l4[3] * Tc[j4 * 4 + 3];
;                 }
;                 Tc[i] = (s0 + s1) + (s2 + s3);
.LBB0_491:
	s_andn2_b64 vcc, exec, s[0:1]
	s_cbranch_vccnz .LBB0_499
	v_ashrrev_i32_e32 v32, 1, v67
	v_and_b32_e32 v34, 1, v67
	v_lshlrev_b32_e32 v33, 8, v32
	v_lshlrev_b32_e32 v35, 6, v34
	v_readlane_b32 s1, v255, 7
	v_lshlrev_b32_e32 v32, 6, v32
	s_add_i32 s2, 0, 0x25000
	v_add3_u32 v33, s1, v33, v35
	ds_read_b128 v[44:47], v33 offset:8192
	ds_read_b128 v[48:51], v33 offset:8208
	ds_read_b128 v[52:55], v33 offset:8224
	ds_read_b128 v[56:59], v33 offset:8240
	v_lshlrev_b32_e32 v34, 5, v34
	s_waitcnt lgkmcnt(3)
	v_bfe_u32 v35, v44, 16, 1
	v_add3_u32 v35, v44, v35, s68
	v_bfe_u32 v37, v45, 16, 1
	v_lshrrev_b32_e32 v35, 16, v35
	v_add3_u32 v37, v45, v37, s68
	v_and_or_b32 v44, v37, s39, v35
	v_bfe_u32 v35, v46, 16, 1
	v_add3_u32 v35, v46, v35, s68
	v_bfe_u32 v37, v47, 16, 1
	v_lshrrev_b32_e32 v35, 16, v35
	v_add3_u32 v37, v47, v37, s68
	v_and_or_b32 v45, v37, s39, v35
	s_waitcnt lgkmcnt(2)
	v_bfe_u32 v35, v48, 16, 1
	v_add3_u32 v35, v48, v35, s68
	v_bfe_u32 v37, v49, 16, 1
	v_lshrrev_b32_e32 v35, 16, v35
	v_add3_u32 v37, v49, v37, s68
	v_and_or_b32 v46, v37, s39, v35
	v_bfe_u32 v35, v50, 16, 1
	v_add3_u32 v35, v50, v35, s68
	v_bfe_u32 v37, v51, 16, 1
	v_lshrrev_b32_e32 v35, 16, v35
	v_add3_u32 v37, v51, v37, s68
	v_and_or_b32 v47, v37, s39, v35
	s_waitcnt lgkmcnt(1)
	v_bfe_u32 v35, v52, 16, 1
	v_add3_u32 v35, v52, v35, s68
	v_bfe_u32 v37, v53, 16, 1
	v_lshrrev_b32_e32 v35, 16, v35
	v_add3_u32 v37, v53, v37, s68
	v_and_or_b32 v48, v37, s39, v35
	v_bfe_u32 v35, v54, 16, 1
	v_add3_u32 v35, v54, v35, s68
	v_bfe_u32 v37, v55, 16, 1
	v_lshrrev_b32_e32 v35, 16, v35
	v_add3_u32 v37, v55, v37, s68
	v_and_or_b32 v49, v37, s39, v35
	s_waitcnt lgkmcnt(0)
	v_bfe_u32 v35, v56, 16, 1
	v_add3_u32 v35, v56, v35, s68
	v_bfe_u32 v37, v57, 16, 1
	v_lshrrev_b32_e32 v35, 16, v35
	v_add3_u32 v37, v57, v37, s68
	v_and_or_b32 v50, v37, s39, v35
	v_bfe_u32 v35, v58, 16, 1
	v_add3_u32 v35, v58, v35, s68
	v_bfe_u32 v37, v59, 16, 1
	v_ashrrev_i32_e32 v36, 5, v67
	v_and_b32_e32 v33, 31, v67
	v_lshrrev_b32_e32 v35, 16, v35
	v_add3_u32 v37, v59, v37, s68
	v_add3_u32 v32, s2, v32, v34
	s_movk_i32 s0, 0x2080
	v_and_or_b32 v51, v37, s39, v35
	ds_write_b128 v32, v[44:47]
	ds_write_b128 v32, v[48:51] offset:16
	v_mul_lo_u32 v32, v36, s0
	v_cmp_eq_u32_e32 vcc, 0, v33
	v_add_u32_e32 v49, s1, v32
	v_mov_b32_e32 v174, v49
	ds_read_b128 v[44:47], v174 offset:256
	v_mov_b64_e32 v[124:125], 0
	v_mov_b64_e32 v[126:127], 0
	v_mov_b64_e32 v[128:129], 0
	v_mov_b64_e32 v[130:131], 0
	v_mov_b64_e32 v[150:151], 0
	v_mov_b64_e32 v[152:153], 0
	v_mov_b64_e32 v[206:207], 0
	v_mov_b64_e32 v[208:209], 0
	v_mov_b64_e32 v[210:211], 0
	v_mov_b64_e32 v[212:213], 0
	v_mov_b64_e32 v[214:215], 0
	v_mov_b64_e32 v[216:217], 0
	v_mov_b64_e32 v[218:219], 0
	v_mov_b64_e32 v[220:221], 0
	v_mov_b64_e32 v[146:147], 0
	v_mov_b64_e32 v[172:173], 0
	v_cndmask_b32_e64 v124, 0, 1.0, vcc
	v_cmp_eq_u32_e32 vcc, 1, v33
	v_mov_b32_e32 v35, 0
	v_mov_b64_e32 v[38:39], 0
	v_cndmask_b32_e64 v34, 0, 1.0, vcc
	v_cmp_eq_u32_e32 vcc, 2, v33
	s_waitcnt lgkmcnt(0)
	v_pk_fma_f32 v[34:35], v[124:125], v[44:45], v[34:35] neg_lo:[1,0,0] neg_hi:[1,0,0]
	v_pk_fma_f32 v[38:39], v[126:127], v[46:47], v[38:39] neg_lo:[1,0,0] neg_hi:[1,0,0]
	ds_read_b128 v[44:47], v174 offset:512
	v_cndmask_b32_e64 v132, 0, 1.0, vcc
	v_mov_b32_e32 v133, 0
	v_mov_b64_e32 v[144:145], 0
	v_add_f32_e32 v122, v34, v35
	v_add_f32_e32 v123, v38, v39
	v_add_f32_e32 v125, v122, v123
	v_cmp_eq_u32_e32 vcc, 3, v33
	s_waitcnt lgkmcnt(0)
	v_pk_fma_f32 v[132:133], v[124:125], v[44:45], v[132:133] neg_lo:[1,0,0] neg_hi:[1,0,0]
	v_pk_fma_f32 v[144:145], v[126:127], v[46:47], v[144:145] neg_lo:[1,0,0] neg_hi:[1,0,0]
	ds_read_b128 v[44:47], v174 offset:768
	v_cndmask_b32_e64 v34, 0, 1.0, vcc
	v_mov_b32_e32 v35, 0
	v_mov_b64_e32 v[38:39], 0
	v_add_f32_e32 v122, v132, v133
	v_add_f32_e32 v123, v144, v145
	v_add_f32_e32 v126, v122, v123
	v_cmp_eq_u32_e32 vcc, 4, v33
	s_waitcnt lgkmcnt(0)
	v_pk_fma_f32 v[34:35], v[124:125], v[44:45], v[34:35] neg_lo:[1,0,0] neg_hi:[1,0,0]
	v_pk_fma_f32 v[38:39], v[126:127], v[46:47], v[38:39] neg_lo:[1,0,0] neg_hi:[1,0,0]
	ds_read_b128 v[44:47], v174 offset:1024
	v_cndmask_b32_e64 v132, 0, 1.0, vcc
	v_mov_b32_e32 v133, 0
	v_mov_b64_e32 v[144:145], 0
	v_add_f32_e32 v122, v34, v35
	v_add_f32_e32 v123, v38, v39
	v_add_f32_e32 v127, v122, v123
	ds_read_b128 v[48:51], v174 offset:1296
	v_cmp_eq_u32_e32 vcc, 5, v33
	s_waitcnt lgkmcnt(1)
	v_pk_fma_f32 v[132:133], v[124:125], v[44:45], v[132:133] neg_lo:[1,0,0] neg_hi:[1,0,0]
	v_pk_fma_f32 v[144:145], v[126:127], v[46:47], v[144:145] neg_lo:[1,0,0] neg_hi:[1,0,0]
	ds_read_b128 v[44:47], v174 offset:1280
	v_cndmask_b32_e64 v34, 0, 1.0, vcc
	v_mov_b32_e32 v35, 0
	v_mov_b64_e32 v[38:39], 0
	v_add_f32_e32 v122, v132, v133
	v_add_f32_e32 v123, v144, v145
	v_add_f32_e32 v128, v122, v123
	v_cmp_eq_u32_e32 vcc, 6, v33
	s_waitcnt lgkmcnt(0)
	v_pk_fma_f32 v[34:35], v[124:125], v[44:45], v[34:35] neg_lo:[1,0,0] neg_hi:[1,0,0]
	v_pk_fma_f32 v[38:39], v[126:127], v[46:47], v[38:39] neg_lo:[1,0,0] neg_hi:[1,0,0]
	ds_read_b128 v[44:47], v174 offset:1536
	v_cndmask_b32_e64 v132, 0, 1.0, vcc
	v_mov_b32_e32 v133, 0
	v_mov_b64_e32 v[144:145], 0
	s_waitcnt lgkmcnt(2)
	v_pk_fma_f32 v[34:35], v[128:129], v[48:49], v[34:35] neg_lo:[1,0,0] neg_hi:[1,0,0]
	v_pk_fma_f32 v[38:39], v[130:131], v[50:51], v[38:39] neg_lo:[1,0,0] neg_hi:[1,0,0]
	ds_read_b128 v[48:51], v174 offset:1552
	v_add_f32_e32 v122, v34, v35
	v_add_f32_e32 v123, v38, v39
	v_add_f32_e32 v129, v122, v123
	v_cmp_eq_u32_e32 vcc, 7, v33
	s_waitcnt lgkmcnt(1)
; #define LAS __attribute__((address_space(3)))
; DI void gdn_unit(const Params& P, bf16_t* proj, const float* gb, int b, int h, LAS unsigned char* lds) {
;     ...
; #pragma unroll
;             for (int i = 0; i < 32; ++i) {
;                 float s0 = (cl == i) ? 1.0f : 0.0f, s1 = 0.f, s2 = 0.f, s3 = 0.f;
;                 f32x4 lr[8];
; #pragma unroll
;                 for (int j4 = 0; j4 < (i + 3) / 4; ++j4) lr[j4] = *(const LAS f32x4*)(Lblk + i * 64 + j4 * 4);
;                 __builtin_amdgcn_sched_barrier(0);
; #pragma unroll
;                 for (int j4 = 0; j4 < (i + 3) / 4; ++j4) {
;                     const f32x4 l4 = lr[j4];
;                     if (j4 * 4 + 0 < i) s0 -= l4[0] * Tc[j4 * 4 + 0];
;                     if (j4 * 4 + 1 < i) s1 -= l4[1] * Tc[j4 * 4 + 1];
;                     if (j4 * 4 + 2 < i) s2 -= l4[2] * Tc[j4 * 4 + 2];
;                     if (j4 * 4 + 3 < i) s3 -= l4[3] * Tc[j4 * 4 + 3];
;                 }
;                 Tc[i] = (s0 + s1) + (s2 + s3);
	v_pk_fma_f32 v[132:133], v[124:125], v[44:45], v[132:133] neg_lo:[1,0,0] neg_hi:[1,0,0]
	v_pk_fma_f32 v[144:145], v[126:127], v[46:47], v[144:145] neg_lo:[1,0,0] neg_hi:[1,0,0]
	ds_read_b128 v[44:47], v174 offset:1792
	v_cndmask_b32_e64 v34, 0, 1.0, vcc
	v_mov_b32_e32 v35, 0
	v_mov_b64_e32 v[38:39], 0
	s_waitcnt lgkmcnt(1)
	v_pk_fma_f32 v[132:133], v[128:129], v[48:49], v[132:133] neg_lo:[1,0,0] neg_hi:[1,0,0]
	v_pk_fma_f32 v[144:145], v[130:131], v[50:51], v[144:145] neg_lo:[1,0,0] neg_hi:[1,0,0]
	ds_read_b128 v[48:51], v174 offset:1808
	v_add_f32_e32 v122, v132, v133
	v_add_f32_e32 v123, v144, v145
	v_add_f32_e32 v130, v122, v123
	v_cmp_eq_u32_e32 vcc, 8, v33
	s_waitcnt lgkmcnt(1)
	v_pk_fma_f32 v[34:35], v[124:125], v[44:45], v[34:35] neg_lo:[1,0,0] neg_hi:[1,0,0]
	v_pk_fma_f32 v[38:39], v[126:127], v[46:47], v[38:39] neg_lo:[1,0,0] neg_hi:[1,0,0]
	ds_read_b128 v[44:47], v174 offset:2048
	v_cndmask_b32_e64 v132, 0, 1.0, vcc
	v_mov_b32_e32 v133, 0
	v_mov_b64_e32 v[144:145], 0
	s_waitcnt lgkmcnt(1)
	v_pk_fma_f32 v[34:35], v[128:129], v[48:49], v[34:35] neg_lo:[1,0,0] neg_hi:[1,0,0]
	v_pk_fma_f32 v[38:39], v[130:131], v[50:51], v[38:39] neg_lo:[1,0,0] neg_hi:[1,0,0]
	ds_read_b128 v[48:51], v174 offset:2064
	v_add_f32_e32 v122, v34, v35
	v_add_f32_e32 v123, v38, v39
	v_add_f32_e32 v131, v122, v123
	ds_read_b128 v[52:55], v174 offset:2336
	v_cmp_eq_u32_e32 vcc, 9, v33
	s_waitcnt lgkmcnt(2)
	v_pk_fma_f32 v[132:133], v[124:125], v[44:45], v[132:133] neg_lo:[1,0,0] neg_hi:[1,0,0]
	v_pk_fma_f32 v[144:145], v[126:127], v[46:47], v[144:145] neg_lo:[1,0,0] neg_hi:[1,0,0]
	ds_read_b128 v[44:47], v174 offset:2304
	v_cndmask_b32_e64 v34, 0, 1.0, vcc
	v_mov_b32_e32 v35, 0
	v_mov_b64_e32 v[38:39], 0
	s_waitcnt lgkmcnt(2)
	v_pk_fma_f32 v[132:133], v[128:129], v[48:49], v[132:133] neg_lo:[1,0,0] neg_hi:[1,0,0]
	v_pk_fma_f32 v[144:145], v[130:131], v[50:51], v[144:145] neg_lo:[1,0,0] neg_hi:[1,0,0]
	ds_read_b128 v[48:51], v174 offset:2320
	v_add_f32_e32 v122, v132, v133
	v_add_f32_e32 v123, v144, v145
	v_add_f32_e32 v150, v122, v123
	v_cmp_eq_u32_e32 vcc, 10, v33
	s_waitcnt lgkmcnt(1)
	v_pk_fma_f32 v[34:35], v[124:125], v[44:45], v[34:35] neg_lo:[1,0,0] neg_hi:[1,0,0]
	v_pk_fma_f32 v[38:39], v[126:127], v[46:47], v[38:39] neg_lo:[1,0,0] neg_hi:[1,0,0]
	ds_read_b128 v[44:47], v174 offset:2560
	v_cndmask_b32_e64 v132, 0, 1.0, vcc
	v_mov_b32_e32 v133, 0
	v_mov_b64_e32 v[144:145], 0
	s_waitcnt lgkmcnt(1)
	v_pk_fma_f32 v[34:35], v[128:129], v[48:49], v[34:35] neg_lo:[1,0,0] neg_hi:[1,0,0]
	v_pk_fma_f32 v[38:39], v[130:131], v[50:51], v[38:39] neg_lo:[1,0,0] neg_hi:[1,0,0]
	ds_read_b128 v[48:51], v174 offset:2576
	s_waitcnt lgkmcnt(4)
	v_pk_fma_f32 v[34:35], v[150:151], v[52:53], v[34:35] neg_lo:[1,0,0] neg_hi:[1,0,0]
	v_pk_fma_f32 v[38:39], v[152:153], v[54:55], v[38:39] neg_lo:[1,0,0] neg_hi:[1,0,0]
	ds_read_b128 v[52:55], v174 offset:2592
	v_add_f32_e32 v122, v34, v35
	v_add_f32_e32 v123, v38, v39
	v_add_f32_e32 v151, v122, v123
	v_cmp_eq_u32_e32 vcc, 11, v33
	s_waitcnt lgkmcnt(2)
	v_pk_fma_f32 v[132:133], v[124:125], v[44:45], v[132:133] neg_lo:[1,0,0] neg_hi:[1,0,0]
	v_pk_fma_f32 v[144:145], v[126:127], v[46:47], v[144:145] neg_lo:[1,0,0] neg_hi:[1,0,0]
	ds_read_b128 v[44:47], v174 offset:2816
	v_cndmask_b32_e64 v34, 0, 1.0, vcc
	v_mov_b32_e32 v35, 0
	v_mov_b64_e32 v[38:39], 0
	s_waitcnt lgkmcnt(2)
	v_pk_fma_f32 v[132:133], v[128:129], v[48:49], v[132:133] neg_lo:[1,0,0] neg_hi:[1,0,0]
	v_pk_fma_f32 v[144:145], v[130:131], v[50:51], v[144:145] neg_lo:[1,0,0] neg_hi:[1,0,0]
	ds_read_b128 v[48:51], v174 offset:2832
	s_waitcnt lgkmcnt(2)
	v_pk_fma_f32 v[132:133], v[150:151], v[52:53], v[132:133] neg_lo:[1,0,0] neg_hi:[1,0,0]
	v_pk_fma_f32 v[144:145], v[152:153], v[54:55], v[144:145] neg_lo:[1,0,0] neg_hi:[1,0,0]
	ds_read_b128 v[52:55], v174 offset:2848
	v_add_f32_e32 v122, v132, v133
	v_add_f32_e32 v123, v144, v145
	v_add_f32_e32 v152, v122, v123
	v_cmp_eq_u32_e32 vcc, 12, v33
	s_waitcnt lgkmcnt(2)
	v_pk_fma_f32 v[34:35], v[124:125], v[44:45], v[34:35] neg_lo:[1,0,0] neg_hi:[1,0,0]
	v_pk_fma_f32 v[38:39], v[126:127], v[46:47], v[38:39] neg_lo:[1,0,0] neg_hi:[1,0,0]
	ds_read_b128 v[44:47], v174 offset:3072
	v_cndmask_b32_e64 v132, 0, 1.0, vcc
	v_mov_b32_e32 v133, 0
	v_mov_b64_e32 v[144:145], 0
	s_waitcnt lgkmcnt(2)
	v_pk_fma_f32 v[34:35], v[128:129], v[48:49], v[34:35] neg_lo:[1,0,0] neg_hi:[1,0,0]
	v_pk_fma_f32 v[38:39], v[130:131], v[50:51], v[38:39] neg_lo:[1,0,0] neg_hi:[1,0,0]
	ds_read_b128 v[48:51], v174 offset:3088
	s_waitcnt lgkmcnt(2)
	v_pk_fma_f32 v[34:35], v[150:151], v[52:53], v[34:35] neg_lo:[1,0,0] neg_hi:[1,0,0]
	v_pk_fma_f32 v[38:39], v[152:153], v[54:55], v[38:39] neg_lo:[1,0,0] neg_hi:[1,0,0]
	ds_read_b128 v[52:55], v174 offset:3104
	v_add_f32_e32 v122, v34, v35
	v_add_f32_e32 v123, v38, v39
	v_add_f32_e32 v153, v122, v123
	ds_read_b128 v[56:59], v174 offset:3376
	v_cmp_eq_u32_e32 vcc, 13, v33
	s_waitcnt lgkmcnt(3)
	v_pk_fma_f32 v[132:133], v[124:125], v[44:45], v[132:133] neg_lo:[1,0,0] neg_hi:[1,0,0]
	v_pk_fma_f32 v[144:145], v[126:127], v[46:47], v[144:145] neg_lo:[1,0,0] neg_hi:[1,0,0]
	ds_read_b128 v[44:47], v174 offset:3328
	v_cndmask_b32_e64 v34, 0, 1.0, vcc
	v_mov_b32_e32 v35, 0
	v_mov_b64_e32 v[38:39], 0
	s_waitcnt lgkmcnt(3)
	v_pk_fma_f32 v[132:133], v[128:129], v[48:49], v[132:133] neg_lo:[1,0,0] neg_hi:[1,0,0]
	v_pk_fma_f32 v[144:145], v[130:131], v[50:51], v[144:145] neg_lo:[1,0,0] neg_hi:[1,0,0]
	ds_read_b128 v[48:51], v174 offset:3344
	s_waitcnt lgkmcnt(3)
; #define LAS __attribute__((address_space(3)))
; DI void gdn_unit(const Params& P, bf16_t* proj, const float* gb, int b, int h, LAS unsigned char* lds) {
;     ...
; #pragma unroll
;             for (int i = 0; i < 32; ++i) {
;                 float s0 = (cl == i) ? 1.0f : 0.0f, s1 = 0.f, s2 = 0.f, s3 = 0.f;
;                 f32x4 lr[8];
; #pragma unroll
;                 for (int j4 = 0; j4 < (i + 3) / 4; ++j4) lr[j4] = *(const LAS f32x4*)(Lblk + i * 64 + j4 * 4);
;                 __builtin_amdgcn_sched_barrier(0);
; #pragma unroll
;                 for (int j4 = 0; j4 < (i + 3) / 4; ++j4) {
;                     const f32x4 l4 = lr[j4];
;                     if (j4 * 4 + 0 < i) s0 -= l4[0] * Tc[j4 * 4 + 0];
;                     if (j4 * 4 + 1 < i) s1 -= l4[1] * Tc[j4 * 4 + 1];
;                     if (j4 * 4 + 2 < i) s2 -= l4[2] * Tc[j4 * 4 + 2];
;                     if (j4 * 4 + 3 < i) s3 -= l4[3] * Tc[j4 * 4 + 3];
;                 }
;                 Tc[i] = (s0 + s1) + (s2 + s3);
	v_pk_fma_f32 v[132:133], v[150:151], v[52:53], v[132:133] neg_lo:[1,0,0] neg_hi:[1,0,0]
	v_pk_fma_f32 v[144:145], v[152:153], v[54:55], v[144:145] neg_lo:[1,0,0] neg_hi:[1,0,0]
	ds_read_b128 v[52:55], v174 offset:3360
	v_add_f32_e32 v122, v132, v133
	v_add_f32_e32 v123, v144, v145
	v_add_f32_e32 v206, v122, v123
	v_cmp_eq_u32_e32 vcc, 14, v33
	s_waitcnt lgkmcnt(2)
	v_pk_fma_f32 v[34:35], v[124:125], v[44:45], v[34:35] neg_lo:[1,0,0] neg_hi:[1,0,0]
	v_pk_fma_f32 v[38:39], v[126:127], v[46:47], v[38:39] neg_lo:[1,0,0] neg_hi:[1,0,0]
	ds_read_b128 v[44:47], v174 offset:3584
	v_cndmask_b32_e64 v132, 0, 1.0, vcc
	v_mov_b32_e32 v133, 0
	v_mov_b64_e32 v[144:145], 0
	s_waitcnt lgkmcnt(2)
	v_pk_fma_f32 v[34:35], v[128:129], v[48:49], v[34:35] neg_lo:[1,0,0] neg_hi:[1,0,0]
	v_pk_fma_f32 v[38:39], v[130:131], v[50:51], v[38:39] neg_lo:[1,0,0] neg_hi:[1,0,0]
	ds_read_b128 v[48:51], v174 offset:3600
	s_waitcnt lgkmcnt(2)
	v_pk_fma_f32 v[34:35], v[150:151], v[52:53], v[34:35] neg_lo:[1,0,0] neg_hi:[1,0,0]
	v_pk_fma_f32 v[38:39], v[152:153], v[54:55], v[38:39] neg_lo:[1,0,0] neg_hi:[1,0,0]
	ds_read_b128 v[52:55], v174 offset:3616
	s_waitcnt lgkmcnt(6)
	v_pk_fma_f32 v[34:35], v[206:207], v[56:57], v[34:35] neg_lo:[1,0,0] neg_hi:[1,0,0]
	v_pk_fma_f32 v[38:39], v[208:209], v[58:59], v[38:39] neg_lo:[1,0,0] neg_hi:[1,0,0]
	ds_read_b128 v[56:59], v174 offset:3632
	v_add_f32_e32 v122, v34, v35
	v_add_f32_e32 v123, v38, v39
	v_add_f32_e32 v207, v122, v123
	v_cmp_eq_u32_e32 vcc, 15, v33
	s_waitcnt lgkmcnt(3)
	v_pk_fma_f32 v[132:133], v[124:125], v[44:45], v[132:133] neg_lo:[1,0,0] neg_hi:[1,0,0]
	v_pk_fma_f32 v[144:145], v[126:127], v[46:47], v[144:145] neg_lo:[1,0,0] neg_hi:[1,0,0]
	ds_read_b128 v[44:47], v174 offset:3840
	v_cndmask_b32_e64 v34, 0, 1.0, vcc
	v_mov_b32_e32 v35, 0
	v_mov_b64_e32 v[38:39], 0
	s_waitcnt lgkmcnt(3)
	v_pk_fma_f32 v[132:133], v[128:129], v[48:49], v[132:133] neg_lo:[1,0,0] neg_hi:[1,0,0]
	v_pk_fma_f32 v[144:145], v[130:131], v[50:51], v[144:145] neg_lo:[1,0,0] neg_hi:[1,0,0]
	ds_read_b128 v[48:51], v174 offset:3856
	s_waitcnt lgkmcnt(3)
	v_pk_fma_f32 v[132:133], v[150:151], v[52:53], v[132:133] neg_lo:[1,0,0] neg_hi:[1,0,0]
	v_pk_fma_f32 v[144:145], v[152:153], v[54:55], v[144:145] neg_lo:[1,0,0] neg_hi:[1,0,0]
	ds_read_b128 v[52:55], v174 offset:3872
	s_waitcnt lgkmcnt(3)
	v_pk_fma_f32 v[132:133], v[206:207], v[56:57], v[132:133] neg_lo:[1,0,0] neg_hi:[1,0,0]
	v_pk_fma_f32 v[144:145], v[208:209], v[58:59], v[144:145] neg_lo:[1,0,0] neg_hi:[1,0,0]
	ds_read_b128 v[56:59], v174 offset:3888
	v_add_f32_e32 v122, v132, v133
	v_add_f32_e32 v123, v144, v145
	v_add_f32_e32 v208, v122, v123
	v_cmp_eq_u32_e32 vcc, 16, v33
	s_waitcnt lgkmcnt(3)
	v_pk_fma_f32 v[34:35], v[124:125], v[44:45], v[34:35] neg_lo:[1,0,0] neg_hi:[1,0,0]
	v_pk_fma_f32 v[38:39], v[126:127], v[46:47], v[38:39] neg_lo:[1,0,0] neg_hi:[1,0,0]
	ds_read_b128 v[44:47], v174 offset:4096
	v_cndmask_b32_e64 v132, 0, 1.0, vcc
	v_mov_b32_e32 v133, 0
	v_mov_b64_e32 v[144:145], 0
	s_waitcnt lgkmcnt(3)
	v_pk_fma_f32 v[34:35], v[128:129], v[48:49], v[34:35] neg_lo:[1,0,0] neg_hi:[1,0,0]
	v_pk_fma_f32 v[38:39], v[130:131], v[50:51], v[38:39] neg_lo:[1,0,0] neg_hi:[1,0,0]
	ds_read_b128 v[48:51], v174 offset:4112
	s_waitcnt lgkmcnt(3)
	v_pk_fma_f32 v[34:35], v[150:151], v[52:53], v[34:35] neg_lo:[1,0,0] neg_hi:[1,0,0]
	v_pk_fma_f32 v[38:39], v[152:153], v[54:55], v[38:39] neg_lo:[1,0,0] neg_hi:[1,0,0]
	ds_read_b128 v[52:55], v174 offset:4128
	s_waitcnt lgkmcnt(3)
	v_pk_fma_f32 v[34:35], v[206:207], v[56:57], v[34:35] neg_lo:[1,0,0] neg_hi:[1,0,0]
	v_pk_fma_f32 v[38:39], v[208:209], v[58:59], v[38:39] neg_lo:[1,0,0] neg_hi:[1,0,0]
	ds_read_b128 v[56:59], v174 offset:4144
	v_add_f32_e32 v122, v34, v35
	v_add_f32_e32 v123, v38, v39
	v_add_f32_e32 v209, v122, v123
	ds_read_b128 v[62:65], v174 offset:4416
	v_cmp_eq_u32_e32 vcc, 17, v33
	s_waitcnt lgkmcnt(4)
	v_pk_fma_f32 v[132:133], v[124:125], v[44:45], v[132:133] neg_lo:[1,0,0] neg_hi:[1,0,0]
	v_pk_fma_f32 v[144:145], v[126:127], v[46:47], v[144:145] neg_lo:[1,0,0] neg_hi:[1,0,0]
	ds_read_b128 v[44:47], v174 offset:4352
	v_cndmask_b32_e64 v34, 0, 1.0, vcc
	v_mov_b32_e32 v35, 0
	v_mov_b64_e32 v[38:39], 0
	s_waitcnt lgkmcnt(4)
	v_pk_fma_f32 v[132:133], v[128:129], v[48:49], v[132:133] neg_lo:[1,0,0] neg_hi:[1,0,0]
	v_pk_fma_f32 v[144:145], v[130:131], v[50:51], v[144:145] neg_lo:[1,0,0] neg_hi:[1,0,0]
	ds_read_b128 v[48:51], v174 offset:4368
	s_waitcnt lgkmcnt(4)
	v_pk_fma_f32 v[132:133], v[150:151], v[52:53], v[132:133] neg_lo:[1,0,0] neg_hi:[1,0,0]
	v_pk_fma_f32 v[144:145], v[152:153], v[54:55], v[144:145] neg_lo:[1,0,0] neg_hi:[1,0,0]
	ds_read_b128 v[52:55], v174 offset:4384
	s_waitcnt lgkmcnt(4)
	v_pk_fma_f32 v[132:133], v[206:207], v[56:57], v[132:133] neg_lo:[1,0,0] neg_hi:[1,0,0]
	v_pk_fma_f32 v[144:145], v[208:209], v[58:59], v[144:145] neg_lo:[1,0,0] neg_hi:[1,0,0]
	ds_read_b128 v[56:59], v174 offset:4400
	v_add_f32_e32 v122, v132, v133
	v_add_f32_e32 v123, v144, v145
	v_add_f32_e32 v210, v122, v123
	v_cmp_eq_u32_e32 vcc, 18, v33
	s_waitcnt lgkmcnt(3)
	v_pk_fma_f32 v[34:35], v[124:125], v[44:45], v[34:35] neg_lo:[1,0,0] neg_hi:[1,0,0]
	v_pk_fma_f32 v[38:39], v[126:127], v[46:47], v[38:39] neg_lo:[1,0,0] neg_hi:[1,0,0]
	ds_read_b128 v[44:47], v174 offset:4608
	v_cndmask_b32_e64 v132, 0, 1.0, vcc
	v_mov_b32_e32 v133, 0
	v_mov_b64_e32 v[144:145], 0
	s_waitcnt lgkmcnt(3)
	v_pk_fma_f32 v[34:35], v[128:129], v[48:49], v[34:35] neg_lo:[1,0,0] neg_hi:[1,0,0]
	v_pk_fma_f32 v[38:39], v[130:131], v[50:51], v[38:39] neg_lo:[1,0,0] neg_hi:[1,0,0]
	ds_read_b128 v[48:51], v174 offset:4624
	s_waitcnt lgkmcnt(3)
; #define LAS __attribute__((address_space(3)))
; DI void gdn_unit(const Params& P, bf16_t* proj, const float* gb, int b, int h, LAS unsigned char* lds) {
;     ...
; #pragma unroll
;             for (int i = 0; i < 32; ++i) {
;                 float s0 = (cl == i) ? 1.0f : 0.0f, s1 = 0.f, s2 = 0.f, s3 = 0.f;
;                 f32x4 lr[8];
; #pragma unroll
;                 for (int j4 = 0; j4 < (i + 3) / 4; ++j4) lr[j4] = *(const LAS f32x4*)(Lblk + i * 64 + j4 * 4);
;                 __builtin_amdgcn_sched_barrier(0);
; #pragma unroll
;                 for (int j4 = 0; j4 < (i + 3) / 4; ++j4) {
;                     const f32x4 l4 = lr[j4];
;                     if (j4 * 4 + 0 < i) s0 -= l4[0] * Tc[j4 * 4 + 0];
;                     if (j4 * 4 + 1 < i) s1 -= l4[1] * Tc[j4 * 4 + 1];
;                     if (j4 * 4 + 2 < i) s2 -= l4[2] * Tc[j4 * 4 + 2];
;                     if (j4 * 4 + 3 < i) s3 -= l4[3] * Tc[j4 * 4 + 3];
;                 }
;                 Tc[i] = (s0 + s1) + (s2 + s3);
	v_pk_fma_f32 v[34:35], v[150:151], v[52:53], v[34:35] neg_lo:[1,0,0] neg_hi:[1,0,0]
	v_pk_fma_f32 v[38:39], v[152:153], v[54:55], v[38:39] neg_lo:[1,0,0] neg_hi:[1,0,0]
	ds_read_b128 v[52:55], v174 offset:4640
	s_waitcnt lgkmcnt(3)
	v_pk_fma_f32 v[34:35], v[206:207], v[56:57], v[34:35] neg_lo:[1,0,0] neg_hi:[1,0,0]
	v_pk_fma_f32 v[38:39], v[208:209], v[58:59], v[38:39] neg_lo:[1,0,0] neg_hi:[1,0,0]
	ds_read_b128 v[56:59], v174 offset:4656
	s_waitcnt lgkmcnt(8)
	v_pk_fma_f32 v[34:35], v[210:211], v[62:63], v[34:35] neg_lo:[1,0,0] neg_hi:[1,0,0]
	v_pk_fma_f32 v[38:39], v[212:213], v[64:65], v[38:39] neg_lo:[1,0,0] neg_hi:[1,0,0]
	ds_read_b128 v[62:65], v174 offset:4672
	v_add_f32_e32 v122, v34, v35
	v_add_f32_e32 v123, v38, v39
	v_add_f32_e32 v211, v122, v123
	v_cmp_eq_u32_e32 vcc, 19, v33
	s_waitcnt lgkmcnt(4)
	v_pk_fma_f32 v[132:133], v[124:125], v[44:45], v[132:133] neg_lo:[1,0,0] neg_hi:[1,0,0]
	v_pk_fma_f32 v[144:145], v[126:127], v[46:47], v[144:145] neg_lo:[1,0,0] neg_hi:[1,0,0]
	ds_read_b128 v[44:47], v174 offset:4864
	v_cndmask_b32_e64 v34, 0, 1.0, vcc
	v_mov_b32_e32 v35, 0
	v_mov_b64_e32 v[38:39], 0
	s_waitcnt lgkmcnt(4)
	v_pk_fma_f32 v[132:133], v[128:129], v[48:49], v[132:133] neg_lo:[1,0,0] neg_hi:[1,0,0]
	v_pk_fma_f32 v[144:145], v[130:131], v[50:51], v[144:145] neg_lo:[1,0,0] neg_hi:[1,0,0]
	ds_read_b128 v[48:51], v174 offset:4880
	s_waitcnt lgkmcnt(4)
	v_pk_fma_f32 v[132:133], v[150:151], v[52:53], v[132:133] neg_lo:[1,0,0] neg_hi:[1,0,0]
	v_pk_fma_f32 v[144:145], v[152:153], v[54:55], v[144:145] neg_lo:[1,0,0] neg_hi:[1,0,0]
	ds_read_b128 v[52:55], v174 offset:4896
	s_waitcnt lgkmcnt(4)
	v_pk_fma_f32 v[132:133], v[206:207], v[56:57], v[132:133] neg_lo:[1,0,0] neg_hi:[1,0,0]
	v_pk_fma_f32 v[144:145], v[208:209], v[58:59], v[144:145] neg_lo:[1,0,0] neg_hi:[1,0,0]
	ds_read_b128 v[56:59], v174 offset:4912
	s_waitcnt lgkmcnt(4)
	v_pk_fma_f32 v[132:133], v[210:211], v[62:63], v[132:133] neg_lo:[1,0,0] neg_hi:[1,0,0]
	v_pk_fma_f32 v[144:145], v[212:213], v[64:65], v[144:145] neg_lo:[1,0,0] neg_hi:[1,0,0]
	ds_read_b128 v[62:65], v174 offset:4928
	v_add_f32_e32 v122, v132, v133
	v_add_f32_e32 v123, v144, v145
	v_add_f32_e32 v212, v122, v123
	v_cmp_eq_u32_e32 vcc, 20, v33
	s_waitcnt lgkmcnt(4)
	v_pk_fma_f32 v[34:35], v[124:125], v[44:45], v[34:35] neg_lo:[1,0,0] neg_hi:[1,0,0]
	v_pk_fma_f32 v[38:39], v[126:127], v[46:47], v[38:39] neg_lo:[1,0,0] neg_hi:[1,0,0]
	ds_read_b128 v[44:47], v174 offset:5120
	v_cndmask_b32_e64 v132, 0, 1.0, vcc
	v_mov_b32_e32 v133, 0
	v_mov_b64_e32 v[144:145], 0
	s_waitcnt lgkmcnt(4)
	v_pk_fma_f32 v[34:35], v[128:129], v[48:49], v[34:35] neg_lo:[1,0,0] neg_hi:[1,0,0]
	v_pk_fma_f32 v[38:39], v[130:131], v[50:51], v[38:39] neg_lo:[1,0,0] neg_hi:[1,0,0]
	ds_read_b128 v[48:51], v174 offset:5136
	s_waitcnt lgkmcnt(4)
	v_pk_fma_f32 v[34:35], v[150:151], v[52:53], v[34:35] neg_lo:[1,0,0] neg_hi:[1,0,0]
	v_pk_fma_f32 v[38:39], v[152:153], v[54:55], v[38:39] neg_lo:[1,0,0] neg_hi:[1,0,0]
	ds_read_b128 v[52:55], v174 offset:5152
	s_waitcnt lgkmcnt(4)
	v_pk_fma_f32 v[34:35], v[206:207], v[56:57], v[34:35] neg_lo:[1,0,0] neg_hi:[1,0,0]
	v_pk_fma_f32 v[38:39], v[208:209], v[58:59], v[38:39] neg_lo:[1,0,0] neg_hi:[1,0,0]
	ds_read_b128 v[56:59], v174 offset:5168
	s_waitcnt lgkmcnt(4)
	v_pk_fma_f32 v[34:35], v[210:211], v[62:63], v[34:35] neg_lo:[1,0,0] neg_hi:[1,0,0]
	v_pk_fma_f32 v[38:39], v[212:213], v[64:65], v[38:39] neg_lo:[1,0,0] neg_hi:[1,0,0]
	ds_read_b128 v[62:65], v174 offset:5184
	v_add_f32_e32 v122, v34, v35
	v_add_f32_e32 v123, v38, v39
	v_add_f32_e32 v213, v122, v123
	ds_read_b128 v[114:117], v174 offset:5456
	v_cmp_eq_u32_e32 vcc, 21, v33
	s_waitcnt lgkmcnt(5)
	v_pk_fma_f32 v[132:133], v[124:125], v[44:45], v[132:133] neg_lo:[1,0,0] neg_hi:[1,0,0]
	v_pk_fma_f32 v[144:145], v[126:127], v[46:47], v[144:145] neg_lo:[1,0,0] neg_hi:[1,0,0]
	ds_read_b128 v[44:47], v174 offset:5376
	v_cndmask_b32_e64 v34, 0, 1.0, vcc
	v_mov_b32_e32 v35, 0
	v_mov_b64_e32 v[38:39], 0
	s_waitcnt lgkmcnt(5)
	v_pk_fma_f32 v[132:133], v[128:129], v[48:49], v[132:133] neg_lo:[1,0,0] neg_hi:[1,0,0]
	v_pk_fma_f32 v[144:145], v[130:131], v[50:51], v[144:145] neg_lo:[1,0,0] neg_hi:[1,0,0]
	ds_read_b128 v[48:51], v174 offset:5392
	s_waitcnt lgkmcnt(5)
	v_pk_fma_f32 v[132:133], v[150:151], v[52:53], v[132:133] neg_lo:[1,0,0] neg_hi:[1,0,0]
	v_pk_fma_f32 v[144:145], v[152:153], v[54:55], v[144:145] neg_lo:[1,0,0] neg_hi:[1,0,0]
	ds_read_b128 v[52:55], v174 offset:5408
	s_waitcnt lgkmcnt(5)
	v_pk_fma_f32 v[132:133], v[206:207], v[56:57], v[132:133] neg_lo:[1,0,0] neg_hi:[1,0,0]
	v_pk_fma_f32 v[144:145], v[208:209], v[58:59], v[144:145] neg_lo:[1,0,0] neg_hi:[1,0,0]
	ds_read_b128 v[56:59], v174 offset:5424
	s_waitcnt lgkmcnt(5)
	v_pk_fma_f32 v[132:133], v[210:211], v[62:63], v[132:133] neg_lo:[1,0,0] neg_hi:[1,0,0]
	v_pk_fma_f32 v[144:145], v[212:213], v[64:65], v[144:145] neg_lo:[1,0,0] neg_hi:[1,0,0]
	ds_read_b128 v[62:65], v174 offset:5440
	v_add_f32_e32 v122, v132, v133
	v_add_f32_e32 v123, v144, v145
	v_add_f32_e32 v214, v122, v123
	v_cmp_eq_u32_e32 vcc, 22, v33
	s_waitcnt lgkmcnt(4)
	v_pk_fma_f32 v[34:35], v[124:125], v[44:45], v[34:35] neg_lo:[1,0,0] neg_hi:[1,0,0]
	v_pk_fma_f32 v[38:39], v[126:127], v[46:47], v[38:39] neg_lo:[1,0,0] neg_hi:[1,0,0]
	ds_read_b128 v[44:47], v174 offset:5632
	v_cndmask_b32_e64 v132, 0, 1.0, vcc
	v_mov_b32_e32 v133, 0
	v_mov_b64_e32 v[144:145], 0
	s_waitcnt lgkmcnt(4)
	v_pk_fma_f32 v[34:35], v[128:129], v[48:49], v[34:35] neg_lo:[1,0,0] neg_hi:[1,0,0]
	v_pk_fma_f32 v[38:39], v[130:131], v[50:51], v[38:39] neg_lo:[1,0,0] neg_hi:[1,0,0]
	ds_read_b128 v[48:51], v174 offset:5648
	s_waitcnt lgkmcnt(4)
; #define LAS __attribute__((address_space(3)))
; DI void gdn_unit(const Params& P, bf16_t* proj, const float* gb, int b, int h, LAS unsigned char* lds) {
;     ...
; #pragma unroll
;             for (int i = 0; i < 32; ++i) {
;                 float s0 = (cl == i) ? 1.0f : 0.0f, s1 = 0.f, s2 = 0.f, s3 = 0.f;
;                 f32x4 lr[8];
; #pragma unroll
;                 for (int j4 = 0; j4 < (i + 3) / 4; ++j4) lr[j4] = *(const LAS f32x4*)(Lblk + i * 64 + j4 * 4);
;                 __builtin_amdgcn_sched_barrier(0);
; #pragma unroll
;                 for (int j4 = 0; j4 < (i + 3) / 4; ++j4) {
;                     const f32x4 l4 = lr[j4];
;                     if (j4 * 4 + 0 < i) s0 -= l4[0] * Tc[j4 * 4 + 0];
;                     if (j4 * 4 + 1 < i) s1 -= l4[1] * Tc[j4 * 4 + 1];
;                     if (j4 * 4 + 2 < i) s2 -= l4[2] * Tc[j4 * 4 + 2];
;                     if (j4 * 4 + 3 < i) s3 -= l4[3] * Tc[j4 * 4 + 3];
;                 }
;                 Tc[i] = (s0 + s1) + (s2 + s3);
	v_pk_fma_f32 v[34:35], v[150:151], v[52:53], v[34:35] neg_lo:[1,0,0] neg_hi:[1,0,0]
	v_pk_fma_f32 v[38:39], v[152:153], v[54:55], v[38:39] neg_lo:[1,0,0] neg_hi:[1,0,0]
	ds_read_b128 v[52:55], v174 offset:5664
	s_waitcnt lgkmcnt(4)
	v_pk_fma_f32 v[34:35], v[206:207], v[56:57], v[34:35] neg_lo:[1,0,0] neg_hi:[1,0,0]
	v_pk_fma_f32 v[38:39], v[208:209], v[58:59], v[38:39] neg_lo:[1,0,0] neg_hi:[1,0,0]
	ds_read_b128 v[56:59], v174 offset:5680
	s_waitcnt lgkmcnt(4)
	v_pk_fma_f32 v[34:35], v[210:211], v[62:63], v[34:35] neg_lo:[1,0,0] neg_hi:[1,0,0]
	v_pk_fma_f32 v[38:39], v[212:213], v[64:65], v[38:39] neg_lo:[1,0,0] neg_hi:[1,0,0]
	ds_read_b128 v[62:65], v174 offset:5696
	s_waitcnt lgkmcnt(10)
	v_pk_fma_f32 v[34:35], v[214:215], v[114:115], v[34:35] neg_lo:[1,0,0] neg_hi:[1,0,0]
	v_pk_fma_f32 v[38:39], v[216:217], v[116:117], v[38:39] neg_lo:[1,0,0] neg_hi:[1,0,0]
	ds_read_b128 v[114:117], v174 offset:5712
	v_add_f32_e32 v122, v34, v35
	v_add_f32_e32 v123, v38, v39
	v_add_f32_e32 v215, v122, v123
	v_cmp_eq_u32_e32 vcc, 23, v33
	s_waitcnt lgkmcnt(5)
	v_pk_fma_f32 v[132:133], v[124:125], v[44:45], v[132:133] neg_lo:[1,0,0] neg_hi:[1,0,0]
	v_pk_fma_f32 v[144:145], v[126:127], v[46:47], v[144:145] neg_lo:[1,0,0] neg_hi:[1,0,0]
	ds_read_b128 v[44:47], v174 offset:5888
	v_cndmask_b32_e64 v34, 0, 1.0, vcc
	v_mov_b32_e32 v35, 0
	v_mov_b64_e32 v[38:39], 0
	s_waitcnt lgkmcnt(5)
	v_pk_fma_f32 v[132:133], v[128:129], v[48:49], v[132:133] neg_lo:[1,0,0] neg_hi:[1,0,0]
	v_pk_fma_f32 v[144:145], v[130:131], v[50:51], v[144:145] neg_lo:[1,0,0] neg_hi:[1,0,0]
	ds_read_b128 v[48:51], v174 offset:5904
	s_waitcnt lgkmcnt(5)
	v_pk_fma_f32 v[132:133], v[150:151], v[52:53], v[132:133] neg_lo:[1,0,0] neg_hi:[1,0,0]
	v_pk_fma_f32 v[144:145], v[152:153], v[54:55], v[144:145] neg_lo:[1,0,0] neg_hi:[1,0,0]
	ds_read_b128 v[52:55], v174 offset:5920
	s_waitcnt lgkmcnt(5)
	v_pk_fma_f32 v[132:133], v[206:207], v[56:57], v[132:133] neg_lo:[1,0,0] neg_hi:[1,0,0]
	v_pk_fma_f32 v[144:145], v[208:209], v[58:59], v[144:145] neg_lo:[1,0,0] neg_hi:[1,0,0]
	ds_read_b128 v[56:59], v174 offset:5936
	s_waitcnt lgkmcnt(5)
	v_pk_fma_f32 v[132:133], v[210:211], v[62:63], v[132:133] neg_lo:[1,0,0] neg_hi:[1,0,0]
	v_pk_fma_f32 v[144:145], v[212:213], v[64:65], v[144:145] neg_lo:[1,0,0] neg_hi:[1,0,0]
	ds_read_b128 v[62:65], v174 offset:5952
	s_waitcnt lgkmcnt(5)
	v_pk_fma_f32 v[132:133], v[214:215], v[114:115], v[132:133] neg_lo:[1,0,0] neg_hi:[1,0,0]
	v_pk_fma_f32 v[144:145], v[216:217], v[116:117], v[144:145] neg_lo:[1,0,0] neg_hi:[1,0,0]
	ds_read_b128 v[114:117], v174 offset:5968
	v_add_f32_e32 v122, v132, v133
	v_add_f32_e32 v123, v144, v145
	v_add_f32_e32 v216, v122, v123
	v_cmp_eq_u32_e32 vcc, 24, v33
	s_waitcnt lgkmcnt(5)
	v_pk_fma_f32 v[34:35], v[124:125], v[44:45], v[34:35] neg_lo:[1,0,0] neg_hi:[1,0,0]
	v_pk_fma_f32 v[38:39], v[126:127], v[46:47], v[38:39] neg_lo:[1,0,0] neg_hi:[1,0,0]
	ds_read_b128 v[44:47], v174 offset:6144
	v_cndmask_b32_e64 v132, 0, 1.0, vcc
	v_mov_b32_e32 v133, 0
	v_mov_b64_e32 v[144:145], 0
	s_waitcnt lgkmcnt(5)
	v_pk_fma_f32 v[34:35], v[128:129], v[48:49], v[34:35] neg_lo:[1,0,0] neg_hi:[1,0,0]
	v_pk_fma_f32 v[38:39], v[130:131], v[50:51], v[38:39] neg_lo:[1,0,0] neg_hi:[1,0,0]
	ds_read_b128 v[48:51], v174 offset:6160
	s_waitcnt lgkmcnt(5)
	v_pk_fma_f32 v[34:35], v[150:151], v[52:53], v[34:35] neg_lo:[1,0,0] neg_hi:[1,0,0]
	v_pk_fma_f32 v[38:39], v[152:153], v[54:55], v[38:39] neg_lo:[1,0,0] neg_hi:[1,0,0]
	ds_read_b128 v[52:55], v174 offset:6176
	s_waitcnt lgkmcnt(5)
	v_pk_fma_f32 v[34:35], v[206:207], v[56:57], v[34:35] neg_lo:[1,0,0] neg_hi:[1,0,0]
	v_pk_fma_f32 v[38:39], v[208:209], v[58:59], v[38:39] neg_lo:[1,0,0] neg_hi:[1,0,0]
	ds_read_b128 v[56:59], v174 offset:6192
	s_waitcnt lgkmcnt(5)
	v_pk_fma_f32 v[34:35], v[210:211], v[62:63], v[34:35] neg_lo:[1,0,0] neg_hi:[1,0,0]
	v_pk_fma_f32 v[38:39], v[212:213], v[64:65], v[38:39] neg_lo:[1,0,0] neg_hi:[1,0,0]
	ds_read_b128 v[62:65], v174 offset:6208
	s_waitcnt lgkmcnt(5)
	v_pk_fma_f32 v[34:35], v[214:215], v[114:115], v[34:35] neg_lo:[1,0,0] neg_hi:[1,0,0]
	v_pk_fma_f32 v[38:39], v[216:217], v[116:117], v[38:39] neg_lo:[1,0,0] neg_hi:[1,0,0]
	ds_read_b128 v[114:117], v174 offset:6224
	v_add_f32_e32 v122, v34, v35
	v_add_f32_e32 v123, v38, v39
	v_add_f32_e32 v217, v122, v123
	ds_read_b128 v[118:121], v174 offset:6496
	v_cmp_eq_u32_e32 vcc, 25, v33
	s_waitcnt lgkmcnt(6)
	v_pk_fma_f32 v[132:133], v[124:125], v[44:45], v[132:133] neg_lo:[1,0,0] neg_hi:[1,0,0]
	v_pk_fma_f32 v[144:145], v[126:127], v[46:47], v[144:145] neg_lo:[1,0,0] neg_hi:[1,0,0]
	ds_read_b128 v[44:47], v174 offset:6400
	v_cndmask_b32_e64 v34, 0, 1.0, vcc
	v_mov_b32_e32 v35, 0
	v_mov_b64_e32 v[38:39], 0
	s_waitcnt lgkmcnt(6)
	v_pk_fma_f32 v[132:133], v[128:129], v[48:49], v[132:133] neg_lo:[1,0,0] neg_hi:[1,0,0]
	v_pk_fma_f32 v[144:145], v[130:131], v[50:51], v[144:145] neg_lo:[1,0,0] neg_hi:[1,0,0]
	ds_read_b128 v[48:51], v174 offset:6416
	s_waitcnt lgkmcnt(6)
	v_pk_fma_f32 v[132:133], v[150:151], v[52:53], v[132:133] neg_lo:[1,0,0] neg_hi:[1,0,0]
	v_pk_fma_f32 v[144:145], v[152:153], v[54:55], v[144:145] neg_lo:[1,0,0] neg_hi:[1,0,0]
	ds_read_b128 v[52:55], v174 offset:6432
	s_waitcnt lgkmcnt(6)
	v_pk_fma_f32 v[132:133], v[206:207], v[56:57], v[132:133] neg_lo:[1,0,0] neg_hi:[1,0,0]
	v_pk_fma_f32 v[144:145], v[208:209], v[58:59], v[144:145] neg_lo:[1,0,0] neg_hi:[1,0,0]
	ds_read_b128 v[56:59], v174 offset:6448
	s_waitcnt lgkmcnt(6)
	v_pk_fma_f32 v[132:133], v[210:211], v[62:63], v[132:133] neg_lo:[1,0,0] neg_hi:[1,0,0]
	v_pk_fma_f32 v[144:145], v[212:213], v[64:65], v[144:145] neg_lo:[1,0,0] neg_hi:[1,0,0]
	ds_read_b128 v[62:65], v174 offset:6464
	s_waitcnt lgkmcnt(6)
; #define LAS __attribute__((address_space(3)))
; DI void gdn_unit(const Params& P, bf16_t* proj, const float* gb, int b, int h, LAS unsigned char* lds) {
;     ...
; #pragma unroll
;             for (int i = 0; i < 32; ++i) {
;                 float s0 = (cl == i) ? 1.0f : 0.0f, s1 = 0.f, s2 = 0.f, s3 = 0.f;
;                 f32x4 lr[8];
; #pragma unroll
;                 for (int j4 = 0; j4 < (i + 3) / 4; ++j4) lr[j4] = *(const LAS f32x4*)(Lblk + i * 64 + j4 * 4);
;                 __builtin_amdgcn_sched_barrier(0);
; #pragma unroll
;                 for (int j4 = 0; j4 < (i + 3) / 4; ++j4) {
;                     const f32x4 l4 = lr[j4];
;                     if (j4 * 4 + 0 < i) s0 -= l4[0] * Tc[j4 * 4 + 0];
;                     if (j4 * 4 + 1 < i) s1 -= l4[1] * Tc[j4 * 4 + 1];
;                     if (j4 * 4 + 2 < i) s2 -= l4[2] * Tc[j4 * 4 + 2];
;                     if (j4 * 4 + 3 < i) s3 -= l4[3] * Tc[j4 * 4 + 3];
;                 }
;                 Tc[i] = (s0 + s1) + (s2 + s3);
	v_pk_fma_f32 v[132:133], v[214:215], v[114:115], v[132:133] neg_lo:[1,0,0] neg_hi:[1,0,0]
	v_pk_fma_f32 v[144:145], v[216:217], v[116:117], v[144:145] neg_lo:[1,0,0] neg_hi:[1,0,0]
	ds_read_b128 v[114:117], v174 offset:6480
	v_add_f32_e32 v122, v132, v133
	v_add_f32_e32 v123, v144, v145
	v_add_f32_e32 v218, v122, v123
	v_cmp_eq_u32_e32 vcc, 26, v33
	s_waitcnt lgkmcnt(5)
	v_pk_fma_f32 v[34:35], v[124:125], v[44:45], v[34:35] neg_lo:[1,0,0] neg_hi:[1,0,0]
	v_pk_fma_f32 v[38:39], v[126:127], v[46:47], v[38:39] neg_lo:[1,0,0] neg_hi:[1,0,0]
	ds_read_b128 v[44:47], v174 offset:6656
	v_cndmask_b32_e64 v132, 0, 1.0, vcc
	v_mov_b32_e32 v133, 0
	v_mov_b64_e32 v[144:145], 0
	s_waitcnt lgkmcnt(5)
	v_pk_fma_f32 v[34:35], v[128:129], v[48:49], v[34:35] neg_lo:[1,0,0] neg_hi:[1,0,0]
	v_pk_fma_f32 v[38:39], v[130:131], v[50:51], v[38:39] neg_lo:[1,0,0] neg_hi:[1,0,0]
	ds_read_b128 v[48:51], v174 offset:6672
	s_waitcnt lgkmcnt(5)
	v_pk_fma_f32 v[34:35], v[150:151], v[52:53], v[34:35] neg_lo:[1,0,0] neg_hi:[1,0,0]
	v_pk_fma_f32 v[38:39], v[152:153], v[54:55], v[38:39] neg_lo:[1,0,0] neg_hi:[1,0,0]
	ds_read_b128 v[52:55], v174 offset:6688
	s_waitcnt lgkmcnt(5)
	v_pk_fma_f32 v[34:35], v[206:207], v[56:57], v[34:35] neg_lo:[1,0,0] neg_hi:[1,0,0]
	v_pk_fma_f32 v[38:39], v[208:209], v[58:59], v[38:39] neg_lo:[1,0,0] neg_hi:[1,0,0]
	ds_read_b128 v[56:59], v174 offset:6704
	s_waitcnt lgkmcnt(5)
	v_pk_fma_f32 v[34:35], v[210:211], v[62:63], v[34:35] neg_lo:[1,0,0] neg_hi:[1,0,0]
	v_pk_fma_f32 v[38:39], v[212:213], v[64:65], v[38:39] neg_lo:[1,0,0] neg_hi:[1,0,0]
	ds_read_b128 v[62:65], v174 offset:6720
	s_waitcnt lgkmcnt(5)
	v_pk_fma_f32 v[34:35], v[214:215], v[114:115], v[34:35] neg_lo:[1,0,0] neg_hi:[1,0,0]
	v_pk_fma_f32 v[38:39], v[216:217], v[116:117], v[38:39] neg_lo:[1,0,0] neg_hi:[1,0,0]
	ds_read_b128 v[114:117], v174 offset:6736
	s_waitcnt lgkmcnt(12)
	v_pk_fma_f32 v[34:35], v[218:219], v[118:119], v[34:35] neg_lo:[1,0,0] neg_hi:[1,0,0]
	v_pk_fma_f32 v[38:39], v[220:221], v[120:121], v[38:39] neg_lo:[1,0,0] neg_hi:[1,0,0]
	ds_read_b128 v[118:121], v174 offset:6752
	v_add_f32_e32 v122, v34, v35
	v_add_f32_e32 v123, v38, v39
	v_add_f32_e32 v219, v122, v123
	v_cmp_eq_u32_e32 vcc, 27, v33
	s_waitcnt lgkmcnt(6)
	v_pk_fma_f32 v[132:133], v[124:125], v[44:45], v[132:133] neg_lo:[1,0,0] neg_hi:[1,0,0]
	v_pk_fma_f32 v[144:145], v[126:127], v[46:47], v[144:145] neg_lo:[1,0,0] neg_hi:[1,0,0]
	ds_read_b128 v[44:47], v174 offset:6912
	v_cndmask_b32_e64 v34, 0, 1.0, vcc
	v_mov_b32_e32 v35, 0
	v_mov_b64_e32 v[38:39], 0
	s_waitcnt lgkmcnt(6)
	v_pk_fma_f32 v[132:133], v[128:129], v[48:49], v[132:133] neg_lo:[1,0,0] neg_hi:[1,0,0]
	v_pk_fma_f32 v[144:145], v[130:131], v[50:51], v[144:145] neg_lo:[1,0,0] neg_hi:[1,0,0]
	ds_read_b128 v[48:51], v174 offset:6928
	s_waitcnt lgkmcnt(6)
	v_pk_fma_f32 v[132:133], v[150:151], v[52:53], v[132:133] neg_lo:[1,0,0] neg_hi:[1,0,0]
	v_pk_fma_f32 v[144:145], v[152:153], v[54:55], v[144:145] neg_lo:[1,0,0] neg_hi:[1,0,0]
	ds_read_b128 v[52:55], v174 offset:6944
	s_waitcnt lgkmcnt(6)
	v_pk_fma_f32 v[132:133], v[206:207], v[56:57], v[132:133] neg_lo:[1,0,0] neg_hi:[1,0,0]
	v_pk_fma_f32 v[144:145], v[208:209], v[58:59], v[144:145] neg_lo:[1,0,0] neg_hi:[1,0,0]
	ds_read_b128 v[56:59], v174 offset:6960
	s_waitcnt lgkmcnt(6)
	v_pk_fma_f32 v[132:133], v[210:211], v[62:63], v[132:133] neg_lo:[1,0,0] neg_hi:[1,0,0]
	v_pk_fma_f32 v[144:145], v[212:213], v[64:65], v[144:145] neg_lo:[1,0,0] neg_hi:[1,0,0]
	ds_read_b128 v[62:65], v174 offset:6976
	s_waitcnt lgkmcnt(6)
	v_pk_fma_f32 v[132:133], v[214:215], v[114:115], v[132:133] neg_lo:[1,0,0] neg_hi:[1,0,0]
	v_pk_fma_f32 v[144:145], v[216:217], v[116:117], v[144:145] neg_lo:[1,0,0] neg_hi:[1,0,0]
	ds_read_b128 v[114:117], v174 offset:6992
	s_waitcnt lgkmcnt(6)
	v_pk_fma_f32 v[132:133], v[218:219], v[118:119], v[132:133] neg_lo:[1,0,0] neg_hi:[1,0,0]
	v_pk_fma_f32 v[144:145], v[220:221], v[120:121], v[144:145] neg_lo:[1,0,0] neg_hi:[1,0,0]
	ds_read_b128 v[118:121], v174 offset:7008
	v_add_f32_e32 v122, v132, v133
	v_add_f32_e32 v123, v144, v145
	v_add_f32_e32 v220, v122, v123
	v_cmp_eq_u32_e32 vcc, 28, v33
	s_waitcnt lgkmcnt(6)
	v_pk_fma_f32 v[34:35], v[124:125], v[44:45], v[34:35] neg_lo:[1,0,0] neg_hi:[1,0,0]
	v_pk_fma_f32 v[38:39], v[126:127], v[46:47], v[38:39] neg_lo:[1,0,0] neg_hi:[1,0,0]
	ds_read_b128 v[44:47], v174 offset:7168
	v_cndmask_b32_e64 v132, 0, 1.0, vcc
	v_mov_b32_e32 v133, 0
	v_mov_b64_e32 v[144:145], 0
	s_waitcnt lgkmcnt(6)
	v_pk_fma_f32 v[34:35], v[128:129], v[48:49], v[34:35] neg_lo:[1,0,0] neg_hi:[1,0,0]
	v_pk_fma_f32 v[38:39], v[130:131], v[50:51], v[38:39] neg_lo:[1,0,0] neg_hi:[1,0,0]
	ds_read_b128 v[48:51], v174 offset:7184
	s_waitcnt lgkmcnt(6)
	v_pk_fma_f32 v[34:35], v[150:151], v[52:53], v[34:35] neg_lo:[1,0,0] neg_hi:[1,0,0]
	v_pk_fma_f32 v[38:39], v[152:153], v[54:55], v[38:39] neg_lo:[1,0,0] neg_hi:[1,0,0]
	ds_read_b128 v[52:55], v174 offset:7200
	s_waitcnt lgkmcnt(6)
	v_pk_fma_f32 v[34:35], v[206:207], v[56:57], v[34:35] neg_lo:[1,0,0] neg_hi:[1,0,0]
	v_pk_fma_f32 v[38:39], v[208:209], v[58:59], v[38:39] neg_lo:[1,0,0] neg_hi:[1,0,0]
	ds_read_b128 v[56:59], v174 offset:7216
	s_waitcnt lgkmcnt(6)
	v_pk_fma_f32 v[34:35], v[210:211], v[62:63], v[34:35] neg_lo:[1,0,0] neg_hi:[1,0,0]
	v_pk_fma_f32 v[38:39], v[212:213], v[64:65], v[38:39] neg_lo:[1,0,0] neg_hi:[1,0,0]
	ds_read_b128 v[62:65], v174 offset:7232
	s_waitcnt lgkmcnt(6)
	v_pk_fma_f32 v[34:35], v[214:215], v[114:115], v[34:35] neg_lo:[1,0,0] neg_hi:[1,0,0]
	v_pk_fma_f32 v[38:39], v[216:217], v[116:117], v[38:39] neg_lo:[1,0,0] neg_hi:[1,0,0]
	ds_read_b128 v[114:117], v174 offset:7248
	s_waitcnt lgkmcnt(6)
; #define LAS __attribute__((address_space(3)))
; DI void gdn_unit(const Params& P, bf16_t* proj, const float* gb, int b, int h, LAS unsigned char* lds) {
;     ...
; #pragma unroll
;             for (int i = 0; i < 32; ++i) {
;                 float s0 = (cl == i) ? 1.0f : 0.0f, s1 = 0.f, s2 = 0.f, s3 = 0.f;
;                 f32x4 lr[8];
; #pragma unroll
;                 for (int j4 = 0; j4 < (i + 3) / 4; ++j4) lr[j4] = *(const LAS f32x4*)(Lblk + i * 64 + j4 * 4);
;                 __builtin_amdgcn_sched_barrier(0);
; #pragma unroll
;                 for (int j4 = 0; j4 < (i + 3) / 4; ++j4) {
;                     const f32x4 l4 = lr[j4];
;                     if (j4 * 4 + 0 < i) s0 -= l4[0] * Tc[j4 * 4 + 0];
;                     if (j4 * 4 + 1 < i) s1 -= l4[1] * Tc[j4 * 4 + 1];
;                     if (j4 * 4 + 2 < i) s2 -= l4[2] * Tc[j4 * 4 + 2];
;                     if (j4 * 4 + 3 < i) s3 -= l4[3] * Tc[j4 * 4 + 3];
;                 }
;                 Tc[i] = (s0 + s1) + (s2 + s3);
	v_pk_fma_f32 v[34:35], v[218:219], v[118:119], v[34:35] neg_lo:[1,0,0] neg_hi:[1,0,0]
	v_pk_fma_f32 v[38:39], v[220:221], v[120:121], v[38:39] neg_lo:[1,0,0] neg_hi:[1,0,0]
	ds_read_b128 v[118:121], v174 offset:7264
	v_add_f32_e32 v122, v34, v35
	v_add_f32_e32 v123, v38, v39
	v_add_f32_e32 v221, v122, v123
	ds_read_b128 v[138:141], v174 offset:7536
	v_cmp_eq_u32_e32 vcc, 29, v33
	s_waitcnt lgkmcnt(7)
	v_pk_fma_f32 v[132:133], v[124:125], v[44:45], v[132:133] neg_lo:[1,0,0] neg_hi:[1,0,0]
	v_pk_fma_f32 v[144:145], v[126:127], v[46:47], v[144:145] neg_lo:[1,0,0] neg_hi:[1,0,0]
	ds_read_b128 v[44:47], v174 offset:7424
	v_cndmask_b32_e64 v34, 0, 1.0, vcc
	v_mov_b32_e32 v35, 0
	v_mov_b64_e32 v[38:39], 0
	s_waitcnt lgkmcnt(7)
	v_pk_fma_f32 v[132:133], v[128:129], v[48:49], v[132:133] neg_lo:[1,0,0] neg_hi:[1,0,0]
	v_pk_fma_f32 v[144:145], v[130:131], v[50:51], v[144:145] neg_lo:[1,0,0] neg_hi:[1,0,0]
	ds_read_b128 v[48:51], v174 offset:7440
	s_waitcnt lgkmcnt(7)
	v_pk_fma_f32 v[132:133], v[150:151], v[52:53], v[132:133] neg_lo:[1,0,0] neg_hi:[1,0,0]
	v_pk_fma_f32 v[144:145], v[152:153], v[54:55], v[144:145] neg_lo:[1,0,0] neg_hi:[1,0,0]
	ds_read_b128 v[52:55], v174 offset:7456
	s_waitcnt lgkmcnt(7)
	v_pk_fma_f32 v[132:133], v[206:207], v[56:57], v[132:133] neg_lo:[1,0,0] neg_hi:[1,0,0]
	v_pk_fma_f32 v[144:145], v[208:209], v[58:59], v[144:145] neg_lo:[1,0,0] neg_hi:[1,0,0]
	ds_read_b128 v[56:59], v174 offset:7472
	s_waitcnt lgkmcnt(7)
	v_pk_fma_f32 v[132:133], v[210:211], v[62:63], v[132:133] neg_lo:[1,0,0] neg_hi:[1,0,0]
	v_pk_fma_f32 v[144:145], v[212:213], v[64:65], v[144:145] neg_lo:[1,0,0] neg_hi:[1,0,0]
	ds_read_b128 v[62:65], v174 offset:7488
	s_waitcnt lgkmcnt(7)
	v_pk_fma_f32 v[132:133], v[214:215], v[114:115], v[132:133] neg_lo:[1,0,0] neg_hi:[1,0,0]
	v_pk_fma_f32 v[144:145], v[216:217], v[116:117], v[144:145] neg_lo:[1,0,0] neg_hi:[1,0,0]
	ds_read_b128 v[114:117], v174 offset:7504
	s_waitcnt lgkmcnt(7)
	v_pk_fma_f32 v[132:133], v[218:219], v[118:119], v[132:133] neg_lo:[1,0,0] neg_hi:[1,0,0]
	v_pk_fma_f32 v[144:145], v[220:221], v[120:121], v[144:145] neg_lo:[1,0,0] neg_hi:[1,0,0]
	ds_read_b128 v[118:121], v174 offset:7520
	v_add_f32_e32 v122, v132, v133
	v_add_f32_e32 v123, v144, v145
	v_add_f32_e32 v146, v122, v123
	v_cmp_eq_u32_e32 vcc, 30, v33
	s_waitcnt lgkmcnt(6)
	v_pk_fma_f32 v[34:35], v[124:125], v[44:45], v[34:35] neg_lo:[1,0,0] neg_hi:[1,0,0]
	v_pk_fma_f32 v[38:39], v[126:127], v[46:47], v[38:39] neg_lo:[1,0,0] neg_hi:[1,0,0]
	ds_read_b128 v[44:47], v174 offset:7680
	v_cndmask_b32_e64 v132, 0, 1.0, vcc
	v_mov_b32_e32 v133, 0
	v_mov_b64_e32 v[144:145], 0
	s_waitcnt lgkmcnt(6)
	v_pk_fma_f32 v[34:35], v[128:129], v[48:49], v[34:35] neg_lo:[1,0,0] neg_hi:[1,0,0]
	v_pk_fma_f32 v[38:39], v[130:131], v[50:51], v[38:39] neg_lo:[1,0,0] neg_hi:[1,0,0]
	ds_read_b128 v[48:51], v174 offset:7696
	s_waitcnt lgkmcnt(6)
	v_pk_fma_f32 v[34:35], v[150:151], v[52:53], v[34:35] neg_lo:[1,0,0] neg_hi:[1,0,0]
	v_pk_fma_f32 v[38:39], v[152:153], v[54:55], v[38:39] neg_lo:[1,0,0] neg_hi:[1,0,0]
	ds_read_b128 v[52:55], v174 offset:7712
	s_waitcnt lgkmcnt(6)
	v_pk_fma_f32 v[34:35], v[206:207], v[56:57], v[34:35] neg_lo:[1,0,0] neg_hi:[1,0,0]
	v_pk_fma_f32 v[38:39], v[208:209], v[58:59], v[38:39] neg_lo:[1,0,0] neg_hi:[1,0,0]
	ds_read_b128 v[56:59], v174 offset:7728
	s_waitcnt lgkmcnt(6)
	v_pk_fma_f32 v[34:35], v[210:211], v[62:63], v[34:35] neg_lo:[1,0,0] neg_hi:[1,0,0]
	v_pk_fma_f32 v[38:39], v[212:213], v[64:65], v[38:39] neg_lo:[1,0,0] neg_hi:[1,0,0]
	ds_read_b128 v[62:65], v174 offset:7744
	s_waitcnt lgkmcnt(6)
	v_pk_fma_f32 v[34:35], v[214:215], v[114:115], v[34:35] neg_lo:[1,0,0] neg_hi:[1,0,0]
	v_pk_fma_f32 v[38:39], v[216:217], v[116:117], v[38:39] neg_lo:[1,0,0] neg_hi:[1,0,0]
	ds_read_b128 v[114:117], v174 offset:7760
	s_waitcnt lgkmcnt(6)
	v_pk_fma_f32 v[34:35], v[218:219], v[118:119], v[34:35] neg_lo:[1,0,0] neg_hi:[1,0,0]
	v_pk_fma_f32 v[38:39], v[220:221], v[120:121], v[38:39] neg_lo:[1,0,0] neg_hi:[1,0,0]
	ds_read_b128 v[118:121], v174 offset:7776
	s_waitcnt lgkmcnt(14)
	v_pk_fma_f32 v[34:35], v[146:147], v[138:139], v[34:35] neg_lo:[1,0,0] neg_hi:[1,0,0]
	v_pk_fma_f32 v[38:39], v[172:173], v[140:141], v[38:39] neg_lo:[1,0,0] neg_hi:[1,0,0]
	ds_read_b128 v[138:141], v174 offset:7792
	v_add_f32_e32 v122, v34, v35
	v_add_f32_e32 v123, v38, v39
	v_add_f32_e32 v147, v122, v123
	v_cmp_eq_u32_e32 vcc, 31, v33
	s_waitcnt lgkmcnt(7)
	v_pk_fma_f32 v[132:133], v[124:125], v[44:45], v[132:133] neg_lo:[1,0,0] neg_hi:[1,0,0]
	v_pk_fma_f32 v[144:145], v[126:127], v[46:47], v[144:145] neg_lo:[1,0,0] neg_hi:[1,0,0]
	ds_read_b128 v[44:47], v174 offset:7936
	v_cndmask_b32_e64 v34, 0, 1.0, vcc
	v_mov_b32_e32 v35, 0
	v_mov_b64_e32 v[38:39], 0
	s_waitcnt lgkmcnt(7)
	v_pk_fma_f32 v[132:133], v[128:129], v[48:49], v[132:133] neg_lo:[1,0,0] neg_hi:[1,0,0]
	v_pk_fma_f32 v[144:145], v[130:131], v[50:51], v[144:145] neg_lo:[1,0,0] neg_hi:[1,0,0]
	ds_read_b128 v[48:51], v174 offset:7952
	s_waitcnt lgkmcnt(7)
	v_pk_fma_f32 v[132:133], v[150:151], v[52:53], v[132:133] neg_lo:[1,0,0] neg_hi:[1,0,0]
	v_pk_fma_f32 v[144:145], v[152:153], v[54:55], v[144:145] neg_lo:[1,0,0] neg_hi:[1,0,0]
	ds_read_b128 v[52:55], v174 offset:7968
	s_waitcnt lgkmcnt(7)
	v_pk_fma_f32 v[132:133], v[206:207], v[56:57], v[132:133] neg_lo:[1,0,0] neg_hi:[1,0,0]
	v_pk_fma_f32 v[144:145], v[208:209], v[58:59], v[144:145] neg_lo:[1,0,0] neg_hi:[1,0,0]
	ds_read_b128 v[56:59], v174 offset:7984
	s_waitcnt lgkmcnt(7)
	v_pk_fma_f32 v[132:133], v[210:211], v[62:63], v[132:133] neg_lo:[1,0,0] neg_hi:[1,0,0]
	v_pk_fma_f32 v[144:145], v[212:213], v[64:65], v[144:145] neg_lo:[1,0,0] neg_hi:[1,0,0]
	ds_read_b128 v[62:65], v174 offset:8000
	s_waitcnt lgkmcnt(7)
; #define LAS __attribute__((address_space(3)))
; DI unsigned f2bf(float f) { unsigned u = __float_as_uint(f); u += 0x7FFFu + ((u >> 16) & 1u); return u >> 16; }
; DI void gdn_unit(const Params& P, bf16_t* proj, const float* gb, int b, int h, LAS unsigned char* lds) {
;     ...
; #pragma unroll
;             for (int i = 0; i < 32; ++i) {
;                 float s0 = (cl == i) ? 1.0f : 0.0f, s1 = 0.f, s2 = 0.f, s3 = 0.f;
;                 f32x4 lr[8];
; #pragma unroll
;                 for (int j4 = 0; j4 < (i + 3) / 4; ++j4) lr[j4] = *(const LAS f32x4*)(Lblk + i * 64 + j4 * 4);
;                 __builtin_amdgcn_sched_barrier(0);
; #pragma unroll
;                 for (int j4 = 0; j4 < (i + 3) / 4; ++j4) {
;                     const f32x4 l4 = lr[j4];
;                     if (j4 * 4 + 0 < i) s0 -= l4[0] * Tc[j4 * 4 + 0];
;                     if (j4 * 4 + 1 < i) s1 -= l4[1] * Tc[j4 * 4 + 1];
;                     if (j4 * 4 + 2 < i) s2 -= l4[2] * Tc[j4 * 4 + 2];
;                     if (j4 * 4 + 3 < i) s3 -= l4[3] * Tc[j4 * 4 + 3];
;                 }
;                 Tc[i] = (s0 + s1) + (s2 + s3);
;             }
;             const float sc1 = beta * egc, sc2 = beta;
; #pragma unroll
;             for (int i = 0; i < 32; ++i) {
;                 const int row = blk * 32 + i;
;                 *(LAS bf16_t*)(lds + TP_OFF + row * 144 + lane * 2) = (bf16_t)f2bf(Tc[i] * sc1);
;                 *(LAS bf16_t*)(lds + TPP_OFF + row * 144 + lane * 2) = (bf16_t)f2bf(Tc[i] * sc2);
;             }
	v_pk_fma_f32 v[132:133], v[214:215], v[114:115], v[132:133] neg_lo:[1,0,0] neg_hi:[1,0,0]
	v_pk_fma_f32 v[144:145], v[216:217], v[116:117], v[144:145] neg_lo:[1,0,0] neg_hi:[1,0,0]
	ds_read_b128 v[114:117], v174 offset:8016
	s_waitcnt lgkmcnt(7)
	v_pk_fma_f32 v[132:133], v[218:219], v[118:119], v[132:133] neg_lo:[1,0,0] neg_hi:[1,0,0]
	v_pk_fma_f32 v[144:145], v[220:221], v[120:121], v[144:145] neg_lo:[1,0,0] neg_hi:[1,0,0]
	ds_read_b128 v[118:121], v174 offset:8032
	s_waitcnt lgkmcnt(7)
	v_pk_fma_f32 v[132:133], v[146:147], v[138:139], v[132:133] neg_lo:[1,0,0] neg_hi:[1,0,0]
	v_pk_fma_f32 v[144:145], v[172:173], v[140:141], v[144:145] neg_lo:[1,0,0] neg_hi:[1,0,0]
	ds_read_b128 v[138:141], v174 offset:8048
	v_add_f32_e32 v122, v132, v133
	v_add_f32_e32 v123, v144, v145
	v_add_f32_e32 v172, v122, v123
	s_waitcnt lgkmcnt(7)
	v_pk_fma_f32 v[34:35], v[124:125], v[44:45], v[34:35] neg_lo:[1,0,0] neg_hi:[1,0,0]
	v_pk_fma_f32 v[38:39], v[126:127], v[46:47], v[38:39] neg_lo:[1,0,0] neg_hi:[1,0,0]
	s_waitcnt lgkmcnt(6)
	v_pk_fma_f32 v[34:35], v[128:129], v[48:49], v[34:35] neg_lo:[1,0,0] neg_hi:[1,0,0]
	v_pk_fma_f32 v[38:39], v[130:131], v[50:51], v[38:39] neg_lo:[1,0,0] neg_hi:[1,0,0]
	s_waitcnt lgkmcnt(5)
	v_pk_fma_f32 v[34:35], v[150:151], v[52:53], v[34:35] neg_lo:[1,0,0] neg_hi:[1,0,0]
	v_pk_fma_f32 v[38:39], v[152:153], v[54:55], v[38:39] neg_lo:[1,0,0] neg_hi:[1,0,0]
	s_waitcnt lgkmcnt(4)
	v_pk_fma_f32 v[34:35], v[206:207], v[56:57], v[34:35] neg_lo:[1,0,0] neg_hi:[1,0,0]
	v_pk_fma_f32 v[38:39], v[208:209], v[58:59], v[38:39] neg_lo:[1,0,0] neg_hi:[1,0,0]
	s_waitcnt lgkmcnt(3)
	v_pk_fma_f32 v[34:35], v[210:211], v[62:63], v[34:35] neg_lo:[1,0,0] neg_hi:[1,0,0]
	v_pk_fma_f32 v[38:39], v[212:213], v[64:65], v[38:39] neg_lo:[1,0,0] neg_hi:[1,0,0]
	s_waitcnt lgkmcnt(2)
	v_pk_fma_f32 v[34:35], v[214:215], v[114:115], v[34:35] neg_lo:[1,0,0] neg_hi:[1,0,0]
	v_pk_fma_f32 v[38:39], v[216:217], v[116:117], v[38:39] neg_lo:[1,0,0] neg_hi:[1,0,0]
	s_waitcnt lgkmcnt(1)
	v_pk_fma_f32 v[34:35], v[218:219], v[118:119], v[34:35] neg_lo:[1,0,0] neg_hi:[1,0,0]
	v_pk_fma_f32 v[38:39], v[220:221], v[120:121], v[38:39] neg_lo:[1,0,0] neg_hi:[1,0,0]
	s_waitcnt lgkmcnt(0)
	v_pk_fma_f32 v[34:35], v[146:147], v[138:139], v[34:35] neg_lo:[1,0,0] neg_hi:[1,0,0]
	v_pk_fma_f32 v[38:39], v[172:173], v[140:141], v[38:39] neg_lo:[1,0,0] neg_hi:[1,0,0]
	v_add_f32_e32 v122, v34, v35
	v_add_f32_e32 v123, v38, v39
	v_add_f32_e32 v173, v122, v123
	v_mov_b32_e32 v37, v124
	v_mov_b32_e32 v32, v125
	v_mov_b32_e32 v34, v126
	v_mov_b32_e32 v35, v127
	v_mov_b32_e32 v39, v128
	v_mov_b32_e32 v38, v129
	v_mov_b32_e32 v43, v130
	v_mov_b32_e32 v44, v131
	v_mov_b32_e32 v45, v150
	v_mov_b32_e32 v47, v151
	v_mov_b32_e32 v46, v152
	v_mov_b32_e32 v48, v153
	v_mov_b32_e32 v50, v206
	v_mov_b32_e32 v52, v207
	v_mov_b32_e32 v51, v208
	v_mov_b32_e32 v53, v209
	v_mov_b32_e32 v54, v210
	v_mov_b32_e32 v56, v211
	v_mov_b32_e32 v55, v212
	v_mov_b32_e32 v57, v213
	v_mov_b32_e32 v58, v214
	v_mov_b32_e32 v62, v215
	v_mov_b32_e32 v59, v216
	v_mov_b32_e32 v63, v217
	v_mov_b32_e32 v64, v218
	v_mov_b32_e32 v114, v219
	v_mov_b32_e32 v65, v220
	v_mov_b32_e32 v115, v221
	v_mov_b32_e32 v49, v146
	v_mov_b32_e32 v117, v147
	v_mov_b32_e32 v116, v172
	v_mov_b32_e32 v118, v173
	v_mul_f32_e32 v119, v108, v109
	v_and_b32_e32 v120, 0xfffffe0, v67
	v_readlane_b32 s0, v255, 9
	v_mul_f32_e32 v121, v37, v119
	v_bfe_u32 v122, v121, 16, 1
	v_add_u32_e32 v109, s0, v60
	v_mul_lo_u32 v120, v120, s37
	v_add3_u32 v121, v121, v122, s68
	v_add_u32_e32 v122, v109, v120
	v_readlane_b32 s0, v255, 10
	ds_write_b16_d16_hi v122, v121
	v_mul_f32_e32 v121, v108, v37
	v_add_u32_e32 v60, s0, v60
	v_bfe_u32 v123, v121, 16, 1
	v_add3_u32 v121, v121, v123, s68
	v_add_u32_e32 v120, v60, v120
	ds_write_b16_d16_hi v120, v121
	v_mul_f32_e32 v121, v119, v32
	v_bfe_u32 v123, v121, 16, 1
	v_add3_u32 v121, v121, v123, s68
	ds_write_b16_d16_hi v122, v121 offset:144
	v_mul_f32_e32 v121, v108, v32
	v_bfe_u32 v123, v121, 16, 1
	v_add3_u32 v121, v121, v123, s68
	ds_write_b16_d16_hi v120, v121 offset:144
	v_mul_f32_e32 v121, v119, v34
	v_bfe_u32 v123, v121, 16, 1
	v_add3_u32 v121, v121, v123, s68
	ds_write_b16_d16_hi v122, v121 offset:288
	v_mul_f32_e32 v121, v108, v34
	v_bfe_u32 v123, v121, 16, 1
	v_add3_u32 v121, v121, v123, s68
	ds_write_b16_d16_hi v120, v121 offset:288
	v_mul_f32_e32 v121, v119, v35
	v_bfe_u32 v123, v121, 16, 1
	v_add3_u32 v121, v121, v123, s68
	ds_write_b16_d16_hi v122, v121 offset:432
	v_mul_f32_e32 v121, v108, v35
	v_bfe_u32 v123, v121, 16, 1
	v_add3_u32 v121, v121, v123, s68
	ds_write_b16_d16_hi v120, v121 offset:432
	v_mul_f32_e32 v121, v119, v39
	v_bfe_u32 v123, v121, 16, 1
	v_add3_u32 v121, v121, v123, s68
	ds_write_b16_d16_hi v122, v121 offset:576
	v_mul_f32_e32 v121, v108, v39
	v_bfe_u32 v123, v121, 16, 1
	v_add3_u32 v121, v121, v123, s68
	ds_write_b16_d16_hi v120, v121 offset:576
	v_mul_f32_e32 v121, v119, v38
	v_bfe_u32 v123, v121, 16, 1
	v_add3_u32 v121, v121, v123, s68
	ds_write_b16_d16_hi v122, v121 offset:720
	v_mul_f32_e32 v121, v108, v38
	v_bfe_u32 v123, v121, 16, 1
	v_add3_u32 v121, v121, v123, s68
	ds_write_b16_d16_hi v120, v121 offset:720
	v_mul_f32_e32 v121, v119, v43
	v_bfe_u32 v123, v121, 16, 1
	v_add3_u32 v121, v121, v123, s68
	ds_write_b16_d16_hi v122, v121 offset:864
	v_mul_f32_e32 v121, v108, v43
	v_bfe_u32 v123, v121, 16, 1
	v_add3_u32 v121, v121, v123, s68
	ds_write_b16_d16_hi v120, v121 offset:864
	v_mul_f32_e32 v121, v119, v44
	v_bfe_u32 v123, v121, 16, 1
	v_add3_u32 v121, v121, v123, s68
	ds_write_b16_d16_hi v122, v121 offset:1008
	v_mul_f32_e32 v121, v108, v44
	v_bfe_u32 v123, v121, 16, 1
; #define LAS __attribute__((address_space(3)))
; DI unsigned f2bf(float f) { unsigned u = __float_as_uint(f); u += 0x7FFFu + ((u >> 16) & 1u); return u >> 16; }
; DI void gdn_unit(const Params& P, bf16_t* proj, const float* gb, int b, int h, LAS unsigned char* lds) {
;     ...
;             const float sc1 = beta * egc, sc2 = beta;
; #pragma unroll
;             for (int i = 0; i < 32; ++i) {
;                 const int row = blk * 32 + i;
;                 *(LAS bf16_t*)(lds + TP_OFF + row * 144 + lane * 2) = (bf16_t)f2bf(Tc[i] * sc1);
;                 *(LAS bf16_t*)(lds + TPP_OFF + row * 144 + lane * 2) = (bf16_t)f2bf(Tc[i] * sc2);
;             }
;             if (blk == 1) {
; #pragma unroll
;                 for (int i = 0; i < 32; ++i) { *(LAS bf16_t*)(lds + TP_OFF + i * 144 + lane * 2) = (bf16_t)0; *(LAS bf16_t*)(lds + TPP_OFF + i * 144 + lane * 2) = (bf16_t)0; }
;             }
	v_add3_u32 v121, v121, v123, s68
	ds_write_b16_d16_hi v120, v121 offset:1008
	v_mul_f32_e32 v121, v119, v45
	v_bfe_u32 v123, v121, 16, 1
	v_add3_u32 v121, v121, v123, s68
	ds_write_b16_d16_hi v122, v121 offset:1152
	v_mul_f32_e32 v121, v108, v45
	v_bfe_u32 v123, v121, 16, 1
	v_add3_u32 v121, v121, v123, s68
	ds_write_b16_d16_hi v120, v121 offset:1152
	v_mul_f32_e32 v121, v119, v47
	v_bfe_u32 v123, v121, 16, 1
	v_add3_u32 v121, v121, v123, s68
	ds_write_b16_d16_hi v122, v121 offset:1296
	v_mul_f32_e32 v121, v108, v47
	v_bfe_u32 v123, v121, 16, 1
	v_add3_u32 v121, v121, v123, s68
	ds_write_b16_d16_hi v120, v121 offset:1296
	v_mul_f32_e32 v121, v119, v46
	v_bfe_u32 v123, v121, 16, 1
	v_add3_u32 v121, v121, v123, s68
	ds_write_b16_d16_hi v122, v121 offset:1440
	v_mul_f32_e32 v121, v108, v46
	v_bfe_u32 v123, v121, 16, 1
	v_add3_u32 v121, v121, v123, s68
	ds_write_b16_d16_hi v120, v121 offset:1440
	v_mul_f32_e32 v121, v119, v48
	v_bfe_u32 v123, v121, 16, 1
	v_add3_u32 v121, v121, v123, s68
	ds_write_b16_d16_hi v122, v121 offset:1584
	v_mul_f32_e32 v121, v108, v48
	v_bfe_u32 v123, v121, 16, 1
	v_add3_u32 v121, v121, v123, s68
	ds_write_b16_d16_hi v120, v121 offset:1584
	v_mul_f32_e32 v121, v119, v50
	v_bfe_u32 v123, v121, 16, 1
	v_add3_u32 v121, v121, v123, s68
	ds_write_b16_d16_hi v122, v121 offset:1728
	v_mul_f32_e32 v121, v108, v50
	v_bfe_u32 v123, v121, 16, 1
	v_add3_u32 v121, v121, v123, s68
	ds_write_b16_d16_hi v120, v121 offset:1728
	v_mul_f32_e32 v121, v119, v52
	v_bfe_u32 v123, v121, 16, 1
	v_add3_u32 v121, v121, v123, s68
	ds_write_b16_d16_hi v122, v121 offset:1872
	v_mul_f32_e32 v121, v108, v52
	v_bfe_u32 v123, v121, 16, 1
	v_add3_u32 v121, v121, v123, s68
	ds_write_b16_d16_hi v120, v121 offset:1872
	v_mul_f32_e32 v121, v119, v51
	v_bfe_u32 v123, v121, 16, 1
	v_add3_u32 v121, v121, v123, s68
	ds_write_b16_d16_hi v122, v121 offset:2016
	v_mul_f32_e32 v121, v108, v51
	v_bfe_u32 v123, v121, 16, 1
	v_add3_u32 v121, v121, v123, s68
	ds_write_b16_d16_hi v120, v121 offset:2016
	v_mul_f32_e32 v121, v119, v53
	v_bfe_u32 v123, v121, 16, 1
	v_add3_u32 v121, v121, v123, s68
	ds_write_b16_d16_hi v122, v121 offset:2160
	v_mul_f32_e32 v121, v108, v53
	v_bfe_u32 v123, v121, 16, 1
	v_add3_u32 v121, v121, v123, s68
	ds_write_b16_d16_hi v120, v121 offset:2160
	v_mul_f32_e32 v121, v119, v54
	v_bfe_u32 v123, v121, 16, 1
	v_add3_u32 v121, v121, v123, s68
	ds_write_b16_d16_hi v122, v121 offset:2304
	v_mul_f32_e32 v121, v108, v54
	v_bfe_u32 v123, v121, 16, 1
	v_add3_u32 v121, v121, v123, s68
	ds_write_b16_d16_hi v120, v121 offset:2304
	v_mul_f32_e32 v121, v119, v56
	v_bfe_u32 v123, v121, 16, 1
	v_add3_u32 v121, v121, v123, s68
	ds_write_b16_d16_hi v122, v121 offset:2448
	v_mul_f32_e32 v121, v108, v56
	v_bfe_u32 v123, v121, 16, 1
	v_add3_u32 v121, v121, v123, s68
	ds_write_b16_d16_hi v120, v121 offset:2448
	v_mul_f32_e32 v121, v119, v55
	v_bfe_u32 v123, v121, 16, 1
	v_add3_u32 v121, v121, v123, s68
	ds_write_b16_d16_hi v122, v121 offset:2592
	v_mul_f32_e32 v121, v108, v55
	v_bfe_u32 v123, v121, 16, 1
	v_add3_u32 v121, v121, v123, s68
	ds_write_b16_d16_hi v120, v121 offset:2592
	v_mul_f32_e32 v121, v119, v57
	v_bfe_u32 v123, v121, 16, 1
	v_add3_u32 v121, v121, v123, s68
	ds_write_b16_d16_hi v122, v121 offset:2736
	v_mul_f32_e32 v121, v108, v57
	v_bfe_u32 v123, v121, 16, 1
	v_add3_u32 v121, v121, v123, s68
	ds_write_b16_d16_hi v120, v121 offset:2736
	v_mul_f32_e32 v121, v119, v58
	v_bfe_u32 v123, v121, 16, 1
	v_add3_u32 v121, v121, v123, s68
	ds_write_b16_d16_hi v122, v121 offset:2880
	v_mul_f32_e32 v121, v108, v58
	v_bfe_u32 v123, v121, 16, 1
	v_add3_u32 v121, v121, v123, s68
	ds_write_b16_d16_hi v120, v121 offset:2880
	v_mul_f32_e32 v121, v119, v62
	v_bfe_u32 v123, v121, 16, 1
	v_add3_u32 v121, v121, v123, s68
	ds_write_b16_d16_hi v122, v121 offset:3024
	v_mul_f32_e32 v121, v108, v62
	v_bfe_u32 v123, v121, 16, 1
	v_add3_u32 v121, v121, v123, s68
	ds_write_b16_d16_hi v120, v121 offset:3024
	v_mul_f32_e32 v121, v119, v59
	v_bfe_u32 v123, v121, 16, 1
	v_add3_u32 v121, v121, v123, s68
	ds_write_b16_d16_hi v122, v121 offset:3168
	v_mul_f32_e32 v121, v108, v59
	v_bfe_u32 v123, v121, 16, 1
	v_add3_u32 v121, v121, v123, s68
	ds_write_b16_d16_hi v120, v121 offset:3168
	v_mul_f32_e32 v121, v119, v63
	v_bfe_u32 v123, v121, 16, 1
	v_add3_u32 v121, v121, v123, s68
	ds_write_b16_d16_hi v122, v121 offset:3312
	v_mul_f32_e32 v121, v108, v63
	v_bfe_u32 v123, v121, 16, 1
	v_add3_u32 v121, v121, v123, s68
	ds_write_b16_d16_hi v120, v121 offset:3312
	v_mul_f32_e32 v121, v119, v64
	v_bfe_u32 v123, v121, 16, 1
	v_add3_u32 v121, v121, v123, s68
	ds_write_b16_d16_hi v122, v121 offset:3456
	v_mul_f32_e32 v121, v108, v64
	v_bfe_u32 v123, v121, 16, 1
	v_add3_u32 v121, v121, v123, s68
	ds_write_b16_d16_hi v120, v121 offset:3456
	v_mul_f32_e32 v121, v119, v114
	v_bfe_u32 v123, v121, 16, 1
	v_add3_u32 v121, v121, v123, s68
	ds_write_b16_d16_hi v122, v121 offset:3600
	v_mul_f32_e32 v121, v108, v114
	v_bfe_u32 v123, v121, 16, 1
	v_add3_u32 v121, v121, v123, s68
	ds_write_b16_d16_hi v120, v121 offset:3600
	v_mul_f32_e32 v121, v119, v65
	v_bfe_u32 v123, v121, 16, 1
	v_add3_u32 v121, v121, v123, s68
	ds_write_b16_d16_hi v122, v121 offset:3744
	v_mul_f32_e32 v121, v108, v65
	v_bfe_u32 v123, v121, 16, 1
	v_add3_u32 v121, v121, v123, s68
	ds_write_b16_d16_hi v120, v121 offset:3744
	v_mul_f32_e32 v121, v119, v115
	v_bfe_u32 v123, v121, 16, 1
	v_add3_u32 v121, v121, v123, s68
	ds_write_b16_d16_hi v122, v121 offset:3888
	v_mul_f32_e32 v121, v108, v115
	v_bfe_u32 v123, v121, 16, 1
	v_add3_u32 v121, v121, v123, s68
	ds_write_b16_d16_hi v120, v121 offset:3888
	v_mul_f32_e32 v121, v119, v49
	v_bfe_u32 v123, v121, 16, 1
	v_add3_u32 v121, v121, v123, s68
	ds_write_b16_d16_hi v122, v121 offset:4032
	v_mul_f32_e32 v121, v108, v49
	v_bfe_u32 v123, v121, 16, 1
	v_add3_u32 v121, v121, v123, s68
	ds_write_b16_d16_hi v120, v121 offset:4032
	v_mul_f32_e32 v121, v119, v117
	v_bfe_u32 v123, v121, 16, 1
	v_add3_u32 v121, v121, v123, s68
	ds_write_b16_d16_hi v122, v121 offset:4176
	v_mul_f32_e32 v121, v108, v117
	v_bfe_u32 v123, v121, 16, 1
	v_add3_u32 v121, v121, v123, s68
	ds_write_b16_d16_hi v120, v121 offset:4176
	v_mul_f32_e32 v121, v119, v116
	v_bfe_u32 v123, v121, 16, 1
	v_add3_u32 v121, v121, v123, s68
	ds_write_b16_d16_hi v122, v121 offset:4320
	v_mul_f32_e32 v121, v108, v116
	v_bfe_u32 v122, v121, 16, 1
	v_add3_u32 v121, v121, v122, s68
	ds_write_b16_d16_hi v120, v121 offset:4320
	v_or_b32_e32 v120, 31, v67
	v_mul_f32_e32 v119, v119, v118
	v_bfe_u32 v121, v119, 16, 1
	v_mul_lo_u32 v120, v120, s37
	v_add3_u32 v119, v119, v121, s68
	v_add_u32_e32 v121, v109, v120
	v_mul_f32_e32 v108, v108, v118
	ds_write_b16_d16_hi v121, v119
	v_bfe_u32 v119, v108, 16, 1
	v_add3_u32 v108, v108, v119, s68
	v_add_u32_e32 v119, v60, v120
	v_cmp_eq_u32_e32 vcc, 1, v36
	ds_write_b16_d16_hi v119, v108
	s_and_saveexec_b64 s[0:1], vcc
	s_cbranch_execz .LBB0_494
; #define LAS __attribute__((address_space(3)))
; DI void gdn_unit(const Params& P, bf16_t* proj, const float* gb, int b, int h, LAS unsigned char* lds) {
;     ...
;             if (blk == 1) {
; #pragma unroll
;                 for (int i = 0; i < 32; ++i) { *(LAS bf16_t*)(lds + TP_OFF + i * 144 + lane * 2) = (bf16_t)0; *(LAS bf16_t*)(lds + TPP_OFF + i * 144 + lane * 2) = (bf16_t)0; }
;             }
	ds_write_b16 v109, v137
	ds_write_b16 v60, v137
	ds_write_b16 v109, v137 offset:144
	ds_write_b16 v60, v137 offset:144
	ds_write_b16 v109, v137 offset:288
	ds_write_b16 v60, v137 offset:288
	ds_write_b16 v109, v137 offset:432
	ds_write_b16 v60, v137 offset:432
	ds_write_b16 v109, v137 offset:576
	ds_write_b16 v60, v137 offset:576
	ds_write_b16 v109, v137 offset:720
	ds_write_b16 v60, v137 offset:720
	ds_write_b16 v109, v137 offset:864
	ds_write_b16 v60, v137 offset:864
	ds_write_b16 v109, v137 offset:1008
	ds_write_b16 v60, v137 offset:1008
	ds_write_b16 v109, v137 offset:1152
	ds_write_b16 v60, v137 offset:1152
	ds_write_b16 v109, v137 offset:1296
	ds_write_b16 v60, v137 offset:1296
	ds_write_b16 v109, v137 offset:1440
	ds_write_b16 v60, v137 offset:1440
	ds_write_b16 v109, v137 offset:1584
	ds_write_b16 v60, v137 offset:1584
	ds_write_b16 v109, v137 offset:1728
	ds_write_b16 v60, v137 offset:1728
	ds_write_b16 v109, v137 offset:1872
	ds_write_b16 v60, v137 offset:1872
	ds_write_b16 v109, v137 offset:2016
	ds_write_b16 v60, v137 offset:2016
	ds_write_b16 v109, v137 offset:2160
	ds_write_b16 v60, v137 offset:2160
	ds_write_b16 v109, v137 offset:2304
	ds_write_b16 v60, v137 offset:2304
	ds_write_b16 v109, v137 offset:2448
	ds_write_b16 v60, v137 offset:2448
	ds_write_b16 v109, v137 offset:2592
	ds_write_b16 v60, v137 offset:2592
	ds_write_b16 v109, v137 offset:2736
	ds_write_b16 v60, v137 offset:2736
	ds_write_b16 v109, v137 offset:2880
	ds_write_b16 v60, v137 offset:2880
	ds_write_b16 v109, v137 offset:3024
	ds_write_b16 v60, v137 offset:3024
	ds_write_b16 v109, v137 offset:3168
	ds_write_b16 v60, v137 offset:3168
	ds_write_b16 v109, v137 offset:3312
	ds_write_b16 v60, v137 offset:3312
	ds_write_b16 v109, v137 offset:3456
	ds_write_b16 v60, v137 offset:3456
	ds_write_b16 v109, v137 offset:3600
	ds_write_b16 v60, v137 offset:3600
	ds_write_b16 v109, v137 offset:3744
	ds_write_b16 v60, v137 offset:3744
	ds_write_b16 v109, v137 offset:3888
	ds_write_b16 v60, v137 offset:3888
	ds_write_b16 v109, v137 offset:4032
	ds_write_b16 v60, v137 offset:4032
	ds_write_b16 v109, v137 offset:4176
	ds_write_b16 v60, v137 offset:4176
	ds_write_b16 v109, v137 offset:4320
	ds_write_b16 v60, v137 offset:4320
	ds_write_b16 v109, v137 offset:4464
	ds_write_b16 v60, v137 offset:4464
